# non-temporal (nt) hint on read-once streaming loads: phase-0 f32 weight tiles, phase-1 x rows, phase-4 residual rows, phase-5 x2 rows, phase-8 epilogue x2/Y0 rows
# speedup vs baseline: 1.0113x; 1.0113x over previous
; DI unsigned pk2(float a, float b) { fl2_t f = {a, b}; bf2_t r = __builtin_convertvector(f, bf2_t); return __builtin_bit_cast(unsigned, r); }
; DI void transpose_tile(const float* __restrict__ src, bfr* __restrict__ dst, int K, int N, int k0, int n0, float* lds, int tid) {
; #pragma unroll
;   for (int ps = 0; ps < 4; ++ps) {
;     int kk = ps * 16 + (tid >> 4), n4 = (tid & 15) * 4;
;     float4 v = *(const float4*)(src + (size_t)(k0 + kk) * N + n0 + n4);
;     lds[kk * 65 + n4 + 0] = v.x; lds[kk * 65 + n4 + 1] = v.y; lds[kk * 65 + n4 + 2] = v.z; lds[kk * 65 + n4 + 3] = v.w;
;   }
;   __syncthreads();
; #pragma unroll
;   for (int ps = 0; ps < 2; ++ps) {
;     int nn = ps * 32 + (tid >> 3), kc = (tid & 7) * 8;
;     u32x4 o;
;     o[0] = pk2(lds[(kc + 0) * 65 + nn], lds[(kc + 1) * 65 + nn]);
;     o[1] = pk2(lds[(kc + 2) * 65 + nn], lds[(kc + 3) * 65 + nn]);
;     o[2] = pk2(lds[(kc + 4) * 65 + nn], lds[(kc + 5) * 65 + nn]);
;     o[3] = pk2(lds[(kc + 6) * 65 + nn], lds[(kc + 7) * 65 + nn]);
;     *(u32x4*)(dst + ((size_t)((k0 + kc) >> 5) * N + (n0 + nn)) * 32 + ((k0 + kc) & 31)) = o;
;   }
;   __syncthreads();
; }
; DI void phase0(const Params& p, char* lds0) {
;     ...
;       } else if (it < n_in + n_out + n_gu) {
;         int i2 = it - n_in - n_out; int e = i2 >> 8, r = i2 & 255; int kt = r >> 4, nt = r & 15;
;         transpose_tile(p.w_gu + (size_t)e * 1024 * 1024, (bfr*)(ws + WS_WGU) + (size_t)e * 1024 * 1024, 1024, 1024, kt * 64, nt * 64, tl, tid);
;       } else {
;         int i2 = it - n_in - n_out - n_gu; int e = i2 >> 7, r = i2 & 127; int kt = r >> 4, nt = r & 15;
;         transpose_tile(p.w_d + (size_t)e * 512 * 1024, (bfr*)(ws + WS_WD) + (size_t)e * 1024 * 512, 512, 1024, kt * 64, nt * 64, tl, tid);
.LBB0_47:
	v_cmp_lt_i32_e32 vcc, s16, v31
	s_and_saveexec_b64 s[8:9], vcc
	s_xor_b64 s[8:9], exec, s[8:9]
	s_cbranch_execz .LBB0_57
	v_cmp_lt_u32_e32 vcc, s17, v31
	s_and_saveexec_b64 s[10:11], vcc
	s_xor_b64 s[10:11], exec, s[10:11]
	s_cbranch_execz .LBB0_54
	v_cmp_lt_u32_e32 vcc, s18, v31
	s_and_saveexec_b64 s[12:13], vcc
	s_xor_b64 s[12:13], exec, s[12:13]
	s_cbranch_execz .LBB0_51
	v_add_u32_e32 v2, 0xffffdc80, v31
	v_lshrrev_b32_e32 v2, 7, v2
	v_lshlrev_b64 v[34:35], 21, v[2:3]
	v_and_b32_e32 v53, 0x3c0, v32
	v_lshl_add_u64 v[34:35], s[6:7], 0, v[34:35]
	v_lshlrev_b64 v[50:51], 20, v[2:3]
	v_and_b32_e32 v52, 0x1c0, v1
	v_lshlrev_b32_e32 v2, 2, v53
	v_lshl_add_u64 v[34:35], v[34:35], 0, v[2:3]
	v_mov_b32_e32 v17, v3
	v_or_b32_e32 v2, v52, v18
	v_lshl_add_u64 v[46:47], v[34:35], 0, v[16:17]
	v_lshlrev_b32_e32 v2, 12, v2
	v_lshl_add_u64 v[42:43], v[46:47], 0, v[2:3]
	v_or_b32_e32 v2, v52, v20
	v_lshlrev_b32_e32 v2, 12, v2
	v_lshl_add_u64 v[44:45], v[46:47], 0, v[2:3]
	global_load_dwordx4 v[34:37], v[42:43], off nt
	global_load_dwordx4 v[38:41], v[44:45], off nt
	v_or_b32_e32 v2, v52, v22
	v_lshlrev_b32_e32 v2, 12, v2
	v_lshl_add_u64 v[42:43], v[46:47], 0, v[2:3]
	v_or_b32_e32 v2, v52, v24
	global_load_dwordx4 v[42:45], v[42:43], off nt
	v_lshlrev_b32_e32 v2, 12, v2
	v_lshl_add_u64 v[46:47], v[46:47], 0, v[2:3]
	global_load_dwordx4 v[46:49], v[46:47], off nt
	v_or_b32_e32 v2, v52, v27
	v_lshlrev_b32_e32 v2, 5, v2
	v_and_b32_e32 v2, 0x3c00, v2
	v_or3_b32 v17, v26, v53, v2
	v_lshl_add_u64 v[50:51], v[4:5], 0, v[50:51]
	v_or3_b32 v54, v30, v53, v2
	v_lshlrev_b32_e32 v2, 6, v17
	v_lshl_add_u64 v[52:53], v[50:51], 0, v[2:3]
	v_lshlrev_b32_e32 v2, 6, v54
	v_lshl_add_u64 v[50:51], v[50:51], 0, v[2:3]
	s_waitcnt vmcnt(3)
	ds_write2_b32 v19, v34, v35 offset1:1
	ds_write2_b32 v19, v36, v37 offset0:2 offset1:3
	s_waitcnt vmcnt(2)
	ds_write2_b32 v21, v38, v39 offset1:1
	ds_write2_b32 v21, v40, v41 offset0:2 offset1:3
	s_waitcnt vmcnt(1)
	ds_write2_b32 v23, v42, v43 offset1:1
	ds_write2_b32 v23, v44, v45 offset0:2 offset1:3
	s_waitcnt vmcnt(0)
	ds_write2_b32 v25, v46, v47 offset1:1
	ds_write2_b32 v25, v48, v49 offset0:2 offset1:3
	s_waitcnt lgkmcnt(0)
	s_barrier
	ds_read2_b32 v[38:39], v28 offset1:32
	ds_read2_b32 v[40:41], v29 offset0:65 offset1:97
	ds_read2_b32 v[42:43], v29 offset0:130 offset1:162
	ds_read2_b32 v[44:45], v29 offset0:195 offset1:227
	ds_read2_b32 v[46:47], v33 offset0:4 offset1:36
	ds_read2_b32 v[48:49], v33 offset0:69 offset1:101
	ds_read2_b32 v[54:55], v33 offset0:134 offset1:166
	ds_read2_b32 v[56:57], v33 offset0:199 offset1:231
	s_waitcnt lgkmcnt(6)
	v_cvt_pk_bf16_f32 v34, v38, v40
	s_waitcnt lgkmcnt(4)
	v_cvt_pk_bf16_f32 v35, v42, v44
	s_waitcnt lgkmcnt(2)
	v_cvt_pk_bf16_f32 v36, v46, v48
	v_cvt_pk_bf16_f32 v38, v39, v41
	s_waitcnt lgkmcnt(0)
	v_cvt_pk_bf16_f32 v37, v54, v56
	v_cvt_pk_bf16_f32 v39, v43, v45
	v_cvt_pk_bf16_f32 v40, v47, v49
	v_cvt_pk_bf16_f32 v41, v55, v57
	global_store_dwordx4 v[52:53], v[34:37], off
	global_store_dwordx4 v[50:51], v[38:41], off
	s_barrier
.LBB0_51:
	s_andn2_saveexec_b64 s[12:13], s[12:13]
	s_cbranch_execz .LBB0_53
	v_add_u32_e32 v2, 0xfffffc80, v31
	v_lshrrev_b32_e32 v2, 8, v2
	v_lshlrev_b64 v[34:35], 22, v[2:3]
	v_and_b32_e32 v52, 0x3c0, v32
	v_lshl_add_u64 v[34:35], s[4:5], 0, v[34:35]
	v_add_u32_e32 v17, 0xfffff200, v1
	v_lshlrev_b32_e32 v36, 2, v52
	v_mov_b32_e32 v37, v3
	v_and_b32_e32 v50, 0x3c0, v17
	v_lshl_add_u64 v[34:35], v[34:35], 0, v[36:37]
	v_mov_b32_e32 v17, v3
	v_lshl_add_u64 v[46:47], v[34:35], 0, v[16:17]
	v_or_b32_e32 v17, v50, v18
	v_lshlrev_b32_e32 v34, 12, v17
	v_mov_b32_e32 v35, v3
	v_or_b32_e32 v17, v50, v20
	v_lshl_add_u64 v[42:43], v[46:47], 0, v[34:35]
	v_lshlrev_b32_e32 v34, 12, v17
	v_lshl_add_u64 v[44:45], v[46:47], 0, v[34:35]
	global_load_dwordx4 v[34:37], v[42:43], off nt
	global_load_dwordx4 v[38:41], v[44:45], off nt
	v_or_b32_e32 v17, v50, v22
	v_lshlrev_b32_e32 v42, 12, v17
	v_mov_b32_e32 v43, v3
	v_lshl_add_u64 v[42:43], v[46:47], 0, v[42:43]
	v_or_b32_e32 v17, v50, v24
	global_load_dwordx4 v[42:45], v[42:43], off nt
	v_lshlrev_b32_e32 v48, 12, v17
	v_mov_b32_e32 v49, v3
	v_lshl_add_u64 v[46:47], v[46:47], 0, v[48:49]
	global_load_dwordx4 v[46:49], v[46:47], off nt
	v_or_b32_e32 v17, v50, v27
	v_lshlrev_b64 v[50:51], 21, v[2:3]
	v_lshlrev_b32_e32 v2, 5, v17
	v_and_b32_e32 v2, 0x7c00, v2
	v_or3_b32 v17, v26, v52, v2
	v_lshl_add_u64 v[50:51], v[6:7], 0, v[50:51]
	v_or3_b32 v54, v30, v52, v2
	v_lshlrev_b32_e32 v2, 6, v17
	v_lshl_add_u64 v[52:53], v[50:51], 0, v[2:3]
	v_lshlrev_b32_e32 v2, 6, v54
	v_lshl_add_u64 v[50:51], v[50:51], 0, v[2:3]
	s_waitcnt vmcnt(3)
	ds_write2_b32 v19, v34, v35 offset1:1
	ds_write2_b32 v19, v36, v37 offset0:2 offset1:3
	s_waitcnt vmcnt(2)
	ds_write2_b32 v21, v38, v39 offset1:1
	ds_write2_b32 v21, v40, v41 offset0:2 offset1:3
	s_waitcnt vmcnt(1)
	ds_write2_b32 v23, v42, v43 offset1:1
	ds_write2_b32 v23, v44, v45 offset0:2 offset1:3
	s_waitcnt vmcnt(0)
	ds_write2_b32 v25, v46, v47 offset1:1
	ds_write2_b32 v25, v48, v49 offset0:2 offset1:3
	s_waitcnt lgkmcnt(0)
	s_barrier
	ds_read2_b32 v[38:39], v28 offset1:32
	ds_read2_b32 v[40:41], v29 offset0:65 offset1:97
	ds_read2_b32 v[42:43], v29 offset0:130 offset1:162
	ds_read2_b32 v[44:45], v29 offset0:195 offset1:227
	ds_read2_b32 v[46:47], v33 offset0:4 offset1:36
	ds_read2_b32 v[48:49], v33 offset0:69 offset1:101
	ds_read2_b32 v[54:55], v33 offset0:134 offset1:166
	ds_read2_b32 v[56:57], v33 offset0:199 offset1:231
	s_waitcnt lgkmcnt(6)
	v_cvt_pk_bf16_f32 v34, v38, v40
	s_waitcnt lgkmcnt(4)
	v_cvt_pk_bf16_f32 v35, v42, v44
	s_waitcnt lgkmcnt(2)
	v_cvt_pk_bf16_f32 v36, v46, v48
	v_cvt_pk_bf16_f32 v38, v39, v41
	s_waitcnt lgkmcnt(0)
	v_cvt_pk_bf16_f32 v37, v54, v56
	v_cvt_pk_bf16_f32 v39, v43, v45
	v_cvt_pk_bf16_f32 v40, v47, v49
	v_cvt_pk_bf16_f32 v41, v55, v57
	global_store_dwordx4 v[52:53], v[34:37], off
	global_store_dwordx4 v[50:51], v[38:41], off
	s_barrier

; DI unsigned pk2(float a, float b) { fl2_t f = {a, b}; bf2_t r = __builtin_convertvector(f, bf2_t); return __builtin_bit_cast(unsigned, r); }
; DI void transpose_tile(const float* __restrict__ src, bfr* __restrict__ dst, int K, int N, int k0, int n0, float* lds, int tid) {
; #pragma unroll
;   for (int ps = 0; ps < 4; ++ps) {
;     int kk = ps * 16 + (tid >> 4), n4 = (tid & 15) * 4;
;     float4 v = *(const float4*)(src + (size_t)(k0 + kk) * N + n0 + n4);
;     lds[kk * 65 + n4 + 0] = v.x; lds[kk * 65 + n4 + 1] = v.y; lds[kk * 65 + n4 + 2] = v.z; lds[kk * 65 + n4 + 3] = v.w;
;   }
;   __syncthreads();
; #pragma unroll
;   for (int ps = 0; ps < 2; ++ps) {
;     int nn = ps * 32 + (tid >> 3), kc = (tid & 7) * 8;
;     u32x4 o;
;     o[0] = pk2(lds[(kc + 0) * 65 + nn], lds[(kc + 1) * 65 + nn]);
;     o[1] = pk2(lds[(kc + 2) * 65 + nn], lds[(kc + 3) * 65 + nn]);
;     o[2] = pk2(lds[(kc + 4) * 65 + nn], lds[(kc + 5) * 65 + nn]);
;     o[3] = pk2(lds[(kc + 6) * 65 + nn], lds[(kc + 7) * 65 + nn]);
;     *(u32x4*)(dst + ((size_t)((k0 + kc) >> 5) * N + (n0 + nn)) * 32 + ((k0 + kc) & 31)) = o;
;   }
;   __syncthreads();
; }
; DI void phase0(const Params& p, char* lds0) {
;     ...
;       } else if (it < n_in + n_out) {
;         int i2 = it - n_in; int kt = i2 >> 4, nt = i2 & 15;
;         transpose_tile(p.w_out, (bfr*)(ws + WS_WOUT), 1024, 1024, kt * 64, nt * 64, tl, tid);
.LBB0_54:
	s_andn2_saveexec_b64 s[10:11], s[10:11]
	s_cbranch_execz .LBB0_56
	v_and_b32_e32 v2, 0xfc0, v1
	v_and_b32_e32 v54, 0x3c0, v32
	v_add_u32_e32 v17, 0xfffff600, v2
	v_lshlrev_b32_e32 v2, 2, v54
	v_lshl_add_u64 v[46:47], v[12:13], 0, v[2:3]
	v_or_b32_e32 v2, v17, v18
	v_lshlrev_b64 v[34:35], 12, v[2:3]
	v_or_b32_e32 v2, v17, v20
	v_lshl_add_u64 v[42:43], v[46:47], 0, v[34:35]
	v_lshlrev_b64 v[34:35], 12, v[2:3]
	v_lshl_add_u64 v[44:45], v[46:47], 0, v[34:35]
	global_load_dwordx4 v[34:37], v[42:43], off nt
	global_load_dwordx4 v[38:41], v[44:45], off nt
	v_or_b32_e32 v2, v17, v22
	v_lshlrev_b64 v[42:43], 12, v[2:3]
	v_lshl_add_u64 v[42:43], v[46:47], 0, v[42:43]
	v_or_b32_e32 v2, v17, v24
	global_load_dwordx4 v[42:45], v[42:43], off nt
	v_lshlrev_b64 v[48:49], 12, v[2:3]
	v_lshl_add_u64 v[46:47], v[46:47], 0, v[48:49]
	global_load_dwordx4 v[46:49], v[46:47], off nt
	v_or_b32_e32 v2, v17, v27
	v_lshrrev_b32_e32 v2, 5, v2
	v_lshlrev_b64 v[50:51], 10, v[2:3]
	v_or3_b32 v52, v54, v26, v50
	v_or3_b32 v50, v54, v30, v50
	v_mov_b32_e32 v53, v51
	v_lshlrev_b64 v[52:53], 6, v[52:53]
	v_lshlrev_b64 v[50:51], 6, v[50:51]
	v_lshl_add_u64 v[52:53], v[8:9], 0, v[52:53]
	v_lshl_add_u64 v[50:51], v[8:9], 0, v[50:51]
	s_waitcnt vmcnt(3)
	ds_write2_b32 v19, v34, v35 offset1:1
	ds_write2_b32 v19, v36, v37 offset0:2 offset1:3
	s_waitcnt vmcnt(2)
	ds_write2_b32 v21, v38, v39 offset1:1
	ds_write2_b32 v21, v40, v41 offset0:2 offset1:3
	s_waitcnt vmcnt(1)
	ds_write2_b32 v23, v42, v43 offset1:1
	ds_write2_b32 v23, v44, v45 offset0:2 offset1:3
	s_waitcnt vmcnt(0)
	ds_write2_b32 v25, v46, v47 offset1:1
	ds_write2_b32 v25, v48, v49 offset0:2 offset1:3
	s_waitcnt lgkmcnt(0)
	s_barrier
	ds_read2_b32 v[38:39], v28 offset1:32
	ds_read2_b32 v[40:41], v29 offset0:65 offset1:97
	ds_read2_b32 v[42:43], v29 offset0:130 offset1:162
	ds_read2_b32 v[44:45], v29 offset0:195 offset1:227
	ds_read2_b32 v[46:47], v33 offset0:4 offset1:36
	ds_read2_b32 v[48:49], v33 offset0:69 offset1:101
	ds_read2_b32 v[54:55], v33 offset0:134 offset1:166
	ds_read2_b32 v[56:57], v33 offset0:199 offset1:231
	s_waitcnt lgkmcnt(6)
	v_cvt_pk_bf16_f32 v34, v38, v40
	s_waitcnt lgkmcnt(4)
	v_cvt_pk_bf16_f32 v35, v42, v44
	s_waitcnt lgkmcnt(2)
	v_cvt_pk_bf16_f32 v36, v46, v48
	v_cvt_pk_bf16_f32 v38, v39, v41
	s_waitcnt lgkmcnt(0)
	v_cvt_pk_bf16_f32 v37, v54, v56
	v_cvt_pk_bf16_f32 v39, v43, v45
	v_cvt_pk_bf16_f32 v40, v47, v49
	v_cvt_pk_bf16_f32 v41, v55, v57
	global_store_dwordx4 v[52:53], v[34:37], off
	global_store_dwordx4 v[50:51], v[38:41], off
	s_barrier

; DI unsigned pk2(float a, float b) { fl2_t f = {a, b}; bf2_t r = __builtin_convertvector(f, bf2_t); return __builtin_bit_cast(unsigned, r); }
; DI void transpose_tile(const float* __restrict__ src, bfr* __restrict__ dst, int K, int N, int k0, int n0, float* lds, int tid) {
; #pragma unroll
;   for (int ps = 0; ps < 4; ++ps) {
;     int kk = ps * 16 + (tid >> 4), n4 = (tid & 15) * 4;
;     float4 v = *(const float4*)(src + (size_t)(k0 + kk) * N + n0 + n4);
;     lds[kk * 65 + n4 + 0] = v.x; lds[kk * 65 + n4 + 1] = v.y; lds[kk * 65 + n4 + 2] = v.z; lds[kk * 65 + n4 + 3] = v.w;
;   }
;   __syncthreads();
; #pragma unroll
;   for (int ps = 0; ps < 2; ++ps) {
;     int nn = ps * 32 + (tid >> 3), kc = (tid & 7) * 8;
;     u32x4 o;
;     o[0] = pk2(lds[(kc + 0) * 65 + nn], lds[(kc + 1) * 65 + nn]);
;     o[1] = pk2(lds[(kc + 2) * 65 + nn], lds[(kc + 3) * 65 + nn]);
;     o[2] = pk2(lds[(kc + 4) * 65 + nn], lds[(kc + 5) * 65 + nn]);
;     o[3] = pk2(lds[(kc + 6) * 65 + nn], lds[(kc + 7) * 65 + nn]);
;     *(u32x4*)(dst + ((size_t)((k0 + kc) >> 5) * N + (n0 + nn)) * 32 + ((k0 + kc) & 31)) = o;
;   }
;   __syncthreads();
; }
; DI void phase0(const Params& p, char* lds0) {
;     ...
;       if (it < n_in) {
;         int kt = it / 40, nt = it % 40;
;         transpose_tile(p.w_in, (bfr*)(ws + WS_WIN), 1024, 2560, kt * 64, nt * 64, tl, tid);
.LBB0_57:
	s_andn2_saveexec_b64 s[8:9], s[8:9]
	s_cbranch_execz .LBB0_46
	v_mul_hi_i32 v2, v31, s19
	v_lshrrev_b32_e32 v17, 31, v2
	v_ashrrev_i32_e32 v2, 4, v2
	v_add_u32_e32 v2, v2, v17
	v_mul_lo_u32 v17, v2, 40
	v_sub_u32_e32 v17, v31, v17
	v_lshlrev_b32_e32 v50, 6, v17
	v_lshlrev_b32_e32 v2, 6, v2
	v_ashrrev_i32_e32 v51, 31, v50
	v_lshl_add_u64 v[46:47], v[50:51], 2, v[14:15]
	v_or_b32_e32 v17, v2, v18
	v_mad_i64_i32 v[42:43], s[10:11], v17, s20, v[46:47]
	v_or_b32_e32 v17, v2, v20
	v_mad_i64_i32 v[44:45], s[10:11], v17, s20, v[46:47]
	global_load_dwordx4 v[34:37], v[42:43], off nt
	global_load_dwordx4 v[38:41], v[44:45], off nt
	v_or_b32_e32 v17, v2, v22
	v_mad_i64_i32 v[42:43], s[10:11], v17, s20, v[46:47]
	global_load_dwordx4 v[42:45], v[42:43], off nt
	v_or_b32_e32 v17, v2, v24
	v_mad_i64_i32 v[46:47], s[10:11], v17, s20, v[46:47]
	global_load_dwordx4 v[46:49], v[46:47], off nt
	v_or_b32_e32 v2, v2, v27
	v_or_b32_e32 v52, v50, v26
	v_ashrrev_i32_e32 v2, 5, v2
	v_or_b32_e32 v50, v50, v30
	v_ashrrev_i32_e32 v53, 31, v52
	v_ashrrev_i32_e32 v51, 31, v50
	v_mad_i64_i32 v[52:53], s[10:11], v2, s21, v[52:53]
	v_mad_i64_i32 v[50:51], s[10:11], v2, s21, v[50:51]
	v_lshlrev_b64 v[52:53], 6, v[52:53]
	v_lshlrev_b64 v[50:51], 6, v[50:51]
	v_lshl_add_u64 v[52:53], v[10:11], 0, v[52:53]
	v_lshl_add_u64 v[50:51], v[10:11], 0, v[50:51]
	s_waitcnt vmcnt(3)
	ds_write2_b32 v19, v34, v35 offset1:1
	ds_write2_b32 v19, v36, v37 offset0:2 offset1:3
	s_waitcnt vmcnt(2)
	ds_write2_b32 v21, v38, v39 offset1:1
	ds_write2_b32 v21, v40, v41 offset0:2 offset1:3
	s_waitcnt vmcnt(1)
	ds_write2_b32 v23, v42, v43 offset1:1
	ds_write2_b32 v23, v44, v45 offset0:2 offset1:3
	s_waitcnt vmcnt(0)
	ds_write2_b32 v25, v46, v47 offset1:1
	ds_write2_b32 v25, v48, v49 offset0:2 offset1:3
	s_waitcnt lgkmcnt(0)
	s_barrier
	ds_read2_b32 v[38:39], v28 offset1:32
	ds_read2_b32 v[40:41], v29 offset0:65 offset1:97
	ds_read2_b32 v[42:43], v29 offset0:130 offset1:162
	ds_read2_b32 v[44:45], v29 offset0:195 offset1:227
	ds_read2_b32 v[46:47], v33 offset0:4 offset1:36
	ds_read2_b32 v[48:49], v33 offset0:69 offset1:101
	ds_read2_b32 v[54:55], v33 offset0:134 offset1:166
	ds_read2_b32 v[56:57], v33 offset0:199 offset1:231
	s_waitcnt lgkmcnt(6)
	v_cvt_pk_bf16_f32 v34, v38, v40
	s_waitcnt lgkmcnt(4)
	v_cvt_pk_bf16_f32 v35, v42, v44
	s_waitcnt lgkmcnt(2)
	v_cvt_pk_bf16_f32 v36, v46, v48
	v_cvt_pk_bf16_f32 v38, v39, v41
	s_waitcnt lgkmcnt(0)
	v_cvt_pk_bf16_f32 v37, v54, v56
	v_cvt_pk_bf16_f32 v39, v43, v45
	v_cvt_pk_bf16_f32 v40, v47, v49
	v_cvt_pk_bf16_f32 v41, v55, v57
	global_store_dwordx4 v[52:53], v[34:37], off
	global_store_dwordx4 v[50:51], v[38:41], off
	s_barrier
	s_branch .LBB0_46

; DI void phase1(const Params& p) {
;   const int tid = threadIdx.x, w = tid >> 6, lane = tid & 63;
;   const float* mod = (const float*)(p.ws + WS_MOD);
;   bfr* H = (bfr*)(p.ws + WS_H);
;   const int nwv = gridDim.x * 8, per = (T + nwv - 1) / nwv;
;   const int t_begin = (blockIdx.x * 8 + w) * per, t_end = t_begin + per < T ? t_begin + per : T;
;   if (t_begin >= t_end) return;
;   float4 nx[4], csv[4], shv[4];
; #pragma unroll
;   for (int j = 0; j < 4; ++j) nx[j] = *(const float4*)(xrow(p, t_begin) + j * 256 + lane * 4);
;   int cur_br = -1;
.LBB0_74:
	s_lshl_b32 s0, s72, 3
	s_abs_i32 s1, s0
	v_cvt_f32_u32_e32 v1, s1
	s_sub_i32 s4, 0, s1
	s_add_i32 s3, s0, 0x17fff
	s_xor_b32 s0, s3, s0
	v_rcp_iflag_f32_e32 v1, v1
	s_abs_i32 s3, s3
	s_ashr_i32 s0, s0, 31
	v_lshrrev_b32_e32 v2, 6, v18
	v_mul_f32_e32 v1, 0x4f7ffffe, v1
	v_cvt_u32_f32_e32 v1, v1
	s_nop 0
	v_readfirstlane_b32 s5, v1
	s_mul_i32 s4, s4, s5
	s_mul_hi_u32 s4, s5, s4
	s_add_i32 s5, s5, s4
	s_mul_hi_u32 s4, s3, s5
	s_mul_i32 s5, s4, s1
	s_sub_i32 s3, s3, s5
	s_add_i32 s8, s4, 1
	s_sub_i32 s5, s3, s1
	s_cmp_ge_u32 s3, s1
	s_cselect_b32 s4, s8, s4
	s_cselect_b32 s3, s5, s3
	s_add_i32 s5, s4, 1
	s_cmp_ge_u32 s3, s1
	s_cselect_b32 s1, s5, s4
	s_xor_b32 s1, s1, s0
	s_sub_i32 s0, s1, s0
	v_lshl_add_u32 v1, s2, 3, v2
	v_mul_lo_u32 v62, s0, v1
	v_add_u32_e32 v1, s0, v62
	v_min_i32_e32 v1, 0x18000, v1
	v_cmp_lt_i32_e32 vcc, v62, v1
	s_and_saveexec_b64 s[0:1], vcc
	s_cbranch_execz .LBB0_81
	s_load_dwordx4 s[8:11], s[74:75], 0x0
	s_load_dwordx2 s[4:5], s[74:75], 0x30
	v_lshlrev_b32_e32 v2, 2, v18
	s_mov_b32 s3, 0x10000
	v_and_b32_e32 v20, 0xfc, v2
	s_waitcnt lgkmcnt(0)
	v_mov_b32_e32 v2, s11
	v_mov_b32_e32 v3, s9
	v_cmp_gt_i32_e32 vcc, s3, v62
	v_mov_b32_e32 v4, s8
	v_ashrrev_i32_e32 v63, 31, v62
	v_cndmask_b32_e32 v3, v2, v3, vcc
	v_mov_b32_e32 v2, s10
	v_cndmask_b32_e32 v2, v2, v4, vcc
	v_add_u32_e32 v4, 0xffff0000, v62
	v_cndmask_b32_e32 v5, 0, v63, vcc
	v_cndmask_b32_e32 v4, v4, v62, vcc
	v_lshlrev_b64 v[4:5], 12, v[4:5]
	v_mov_b32_e32 v51, 0
	v_lshl_add_u64 v[2:3], v[2:3], 0, v[4:5]
	v_lshlrev_b32_e32 v50, 2, v20
	v_lshl_add_u64 v[22:23], v[2:3], 0, v[50:51]
	global_load_dwordx4 v[2:5], v[22:23], off offset:3072 nt
	global_load_dwordx4 v[6:9], v[22:23], off offset:2048 nt
	global_load_dwordx4 v[10:13], v[22:23], off offset:1024 nt
	global_load_dwordx4 v[14:17], v[22:23], off nt
	v_mbcnt_lo_u32_b32 v19, -1, 0
	v_mbcnt_hi_u32_b32 v19, -1, v19
	v_and_b32_e32 v21, 64, v19
	v_add_u32_e32 v21, 64, v21
	v_xor_b32_e32 v22, 32, v19
	v_cmp_lt_i32_e32 vcc, v22, v21
	s_load_dwordx2 s[12:13], s[74:75], 0xe0
	v_lshlrev_b64 v[28:29], 11, v[62:63]
	v_cndmask_b32_e32 v22, v19, v22, vcc
	v_lshlrev_b32_e32 v82, 2, v22
	v_xor_b32_e32 v22, 16, v19
	v_cmp_lt_i32_e32 vcc, v22, v21
	v_and_b32_e32 v18, 63, v18
	v_lshl_or_b32 v28, v18, 3, v28
	v_cndmask_b32_e32 v22, v19, v22, vcc
	v_lshlrev_b32_e32 v83, 2, v22
	v_xor_b32_e32 v22, 8, v19
	v_cmp_lt_i32_e32 vcc, v22, v21
	v_or_b32_e32 v24, 0x200, v20
	v_or_b32_e32 v26, 0x300, v20
	v_cndmask_b32_e32 v22, v19, v22, vcc
	v_lshlrev_b32_e32 v84, 2, v22
	v_xor_b32_e32 v22, 4, v19
	v_cmp_lt_i32_e32 vcc, v22, v21
	v_lshl_add_u64 v[52:53], s[4:5], 0, v[50:51]
	s_mov_b64 s[4:5], 0x6894400
	v_cndmask_b32_e32 v22, v19, v22, vcc
	v_lshlrev_b32_e32 v85, 2, v22
	v_xor_b32_e32 v22, 2, v19
	v_cmp_lt_i32_e32 vcc, v22, v21
	v_mov_b32_e32 v57, -1
	s_mov_b64 s[14:15], 0
	v_cndmask_b32_e32 v22, v19, v22, vcc
	v_lshlrev_b32_e32 v86, 2, v22
	v_xor_b32_e32 v22, 1, v19
	v_cmp_lt_i32_e32 vcc, v22, v21
	s_mov_b64 s[16:17], 0x1000
	v_lshlrev_b32_e32 v58, 2, v24
	v_cndmask_b32_e32 v19, v19, v22, vcc
	v_lshlrev_b32_e32 v87, 2, v19
	v_or_b32_e32 v22, 0x100, v20
	s_waitcnt lgkmcnt(0)
	v_lshl_add_u64 v[18:19], s[12:13], 0, v[28:29]
	v_lshl_add_u64 v[54:55], v[18:19], 0, s[4:5]
	v_lshlrev_b32_e32 v56, 2, v22
	v_lshlrev_b32_e32 v60, 2, v26
	s_mov_b32 s22, 0xffff
	v_mov_b32_e32 v88, 0x358637bd
	s_mov_b32 s23, 0x800000
	s_mov_b64 s[18:19], 0x800
	v_lshlrev_b32_e32 v50, 2, v20
	s_branch .LBB0_77

; DI void phase1(const Params& p) {
;     ...
;   for (int t = t_begin; t < t_end; ++t) {
;     int br, s, S; tok_info(t, br, s, S);
;     if (br != cur_br) {
;       cur_br = br;
;       const float* sh = mod + br * 6144, *scl = mod + br * 6144 + 1024;
; #pragma unroll
;       for (int j = 0; j < 4; ++j) {
;         const int c = j * 256 + lane * 4;
;         float4 g = *(const float4*)(p.g_norm1 + c), a = *(const float4*)(scl + c);
;         csv[j] = make_float4(g.x * (1.f + a.x), g.y * (1.f + a.y), g.z * (1.f + a.z), g.w * (1.f + a.w));
;         shv[j] = *(const float4*)(sh + c);
;       }
;     }
;     float4 v[4];
; #pragma unroll
;     for (int j = 0; j < 4; ++j) v[j] = nx[j];
;     if (t + 1 < t_end) {
;       const float* x1 = xrow(p, t + 1);
; #pragma unroll
;       for (int j = 0; j < 4; ++j) nx[j] = *(const float4*)(x1 + j * 256 + lane * 4);
;     }
.LBB0_77:
	v_add_u32_e32 v34, 0xffff0000, v62
	v_lshrrev_b32_e32 v34, 14, v34
	v_add_u32_e32 v34, 16, v34
	v_ashrrev_i32_e32 v35, 12, v62
	v_cmp_gt_i32_e32 vcc, s3, v62
	s_nop 1
	v_cndmask_b32_e32 v34, v34, v35, vcc
	v_cmp_ne_u32_e32 vcc, v34, v57
	s_and_saveexec_b64 s[4:5], vcc
	s_cbranch_execz .LBB0_79
	v_mul_i32_i24_e32 v18, 0x1800, v34
	v_ashrrev_i32_e32 v19, 31, v18
	v_lshl_add_u64 v[18:19], v[18:19], 2, s[12:13]
	v_lshl_add_u64 v[20:21], v[18:19], 0, s[16:17]
	v_lshl_add_u64 v[22:23], v[20:21], 0, v[50:51]
	v_mov_b32_e32 v57, v51
	global_load_dwordx4 v[36:39], v[22:23], off nt
	v_lshl_add_u64 v[22:23], v[20:21], 0, v[56:57]
	v_mov_b32_e32 v59, v51
	global_load_dwordx4 v[40:43], v[22:23], off nt
	v_lshl_add_u64 v[22:23], v[20:21], 0, v[58:59]
	v_mov_b32_e32 v61, v51
	global_load_dwordx4 v[44:47], v[22:23], off nt
	v_lshl_add_u64 v[20:21], v[20:21], 0, v[60:61]
	global_load_dwordx4 v[64:67], v[20:21], off nt
	global_load_dwordx4 v[68:71], v[52:53], off nt
	global_load_dwordx4 v[72:75], v[52:53], off offset:1024 nt
	v_lshl_add_u64 v[48:49], v[18:19], 0, v[50:51]
	global_load_dwordx4 v[76:79], v[52:53], off offset:2048 nt
	global_load_dwordx4 v[18:21], v[48:49], off nt
	global_load_dwordx4 v[90:93], v[52:53], off offset:3072 nt
	global_load_dwordx4 v[22:25], v[48:49], off offset:1024 nt
	global_load_dwordx4 v[26:29], v[48:49], off offset:2048 nt
	global_load_dwordx4 v[30:33], v[48:49], off offset:3072 nt
	v_mov_b32_e32 v57, v34
	s_waitcnt vmcnt(11)
	v_pk_add_f32 v[36:37], v[36:37], 1.0 op_sel_hi:[1,0]
	v_pk_add_f32 v[38:39], v[38:39], 1.0 op_sel_hi:[1,0]
	s_waitcnt vmcnt(10)
	v_pk_add_f32 v[40:41], v[40:41], 1.0 op_sel_hi:[1,0]
	v_pk_add_f32 v[42:43], v[42:43], 1.0 op_sel_hi:[1,0]
	s_waitcnt vmcnt(9)
	v_pk_add_f32 v[44:45], v[44:45], 1.0 op_sel_hi:[1,0]
	v_pk_add_f32 v[46:47], v[46:47], 1.0 op_sel_hi:[1,0]
	s_waitcnt vmcnt(8)
	v_pk_add_f32 v[48:49], v[64:65], 1.0 op_sel_hi:[1,0]
	v_pk_add_f32 v[80:81], v[66:67], 1.0 op_sel_hi:[1,0]
	s_waitcnt vmcnt(7)
	v_pk_mul_f32 v[66:67], v[68:69], v[36:37]
	v_pk_mul_f32 v[64:65], v[70:71], v[38:39]
	s_waitcnt vmcnt(6)
	v_pk_mul_f32 v[70:71], v[72:73], v[40:41]
	v_pk_mul_f32 v[68:69], v[74:75], v[42:43]
	s_waitcnt vmcnt(5)
	v_pk_mul_f32 v[74:75], v[76:77], v[44:45]
	v_pk_mul_f32 v[72:73], v[78:79], v[46:47]
	s_waitcnt vmcnt(3)
	v_pk_mul_f32 v[78:79], v[90:91], v[48:49]
	v_pk_mul_f32 v[76:77], v[92:93], v[80:81]
.LBB0_79:
	s_or_b64 exec, exec, s[4:5]
	v_lshl_add_u64 v[80:81], v[62:63], 0, 1
	v_cmp_lt_i32_e64 s[4:5], v80, v1
	v_cmp_ge_i32_e32 vcc, v80, v1
	s_waitcnt vmcnt(0)
	v_mov_b64_e32 v[34:35], v[14:15]
	v_mov_b64_e32 v[36:37], v[16:17]
	v_mov_b64_e32 v[38:39], v[10:11]
	v_mov_b64_e32 v[40:41], v[12:13]
	v_mov_b64_e32 v[42:43], v[6:7]
	v_mov_b64_e32 v[44:45], v[8:9]
	v_mov_b64_e32 v[46:47], v[2:3]
	v_mov_b64_e32 v[48:49], v[4:5]
	s_and_saveexec_b64 s[20:21], s[4:5]
	s_cbranch_execz .LBB0_76
	v_add_u32_e32 v34, 0xffff0001, v62
	v_cmp_gt_i32_e64 s[4:5], s22, v62
	v_mov_b32_e32 v36, s11
	v_mov_b32_e32 v37, s9
	v_cndmask_b32_e64 v35, 0, v81, s[4:5]
	v_cndmask_b32_e64 v34, v34, v80, s[4:5]
	v_cndmask_b32_e64 v37, v36, v37, s[4:5]
	v_mov_b32_e32 v36, s10
	v_mov_b32_e32 v38, s8
	v_cndmask_b32_e64 v36, v36, v38, s[4:5]
	v_lshlrev_b64 v[34:35], 12, v[34:35]
	v_lshl_add_u64 v[34:35], v[36:37], 0, v[34:35]
	v_lshl_add_u64 v[62:63], v[34:35], 0, v[50:51]
	global_load_dwordx4 v[34:37], v[62:63], off nt
	global_load_dwordx4 v[38:41], v[62:63], off offset:1024 nt
	global_load_dwordx4 v[42:45], v[62:63], off offset:2048 nt
	global_load_dwordx4 v[46:49], v[62:63], off offset:3072 nt
	s_branch .LBB0_76

; #define MFMA(a, b, c) __builtin_amdgcn_mfma_f32_32x32x16_bf16((a), (b), (c), 0, 0, 0)
; DI unsigned pk2(float a, float b) { fl2_t f = {a, b}; bf2_t r = __builtin_convertvector(f, bf2_t); return __builtin_bit_cast(unsigned, r); }
; #define WAIT_V(n) asm volatile("s_waitcnt vmcnt(%0)" ::"n"(n) : "memory")
; #define RAW_BARRIER() do { asm volatile("s_waitcnt lgkmcnt(0)" ::: "memory"); __builtin_amdgcn_s_barrier(); } while (0)
; template <typename FA, typename FB, typename FE>
; DI void gemm_tile(char* lds, int K, int astride, int bstride, FA arow, FB brow, FE epi) {
;     ...
;   for (int kt = 0; kt < nk; ++kt) {
;     if (kt + 2 < nk) WAIT_V(8); else if (kt + 1 < nk) WAIT_V(4); else WAIT_V(0);
;     RAW_BARRIER();
;     if (kt + 3 < nk) stage((kt + 3) & 3, kt + 3);
;     const char* sa = lds + (kt & 3) * 32768 + wm * 4096;
;     const char* sb = lds + (kt & 3) * 32768 + 16384 + wn * 8192;
; #pragma unroll
;     for (int ks = 0; ks < 2; ++ks) {
;       bf16x8 a0 = *(const bf16x8*)(sa + foff[ks]), a1 = *(const bf16x8*)(sa + 2048 + foff[ks]);
; #pragma unroll
;       for (int nt = 0; nt < 4; ++nt) {
;         bf16x8 bb = *(const bf16x8*)(sb + nt * 2048 + foff[ks]);
;         acc[0][nt] = MFMA(a0, bb, acc[0][nt]);
;         acc[1][nt] = MFMA(a1, bb, acc[1][nt]);
;       }
;     }
;   }
;   RAW_BARRIER();
;   bfr* Cs = (bfr*)lds;
; #pragma unroll
;   for (int mt = 0; mt < 2; ++mt)
; #pragma unroll
;     for (int nt = 0; nt < 4; ++nt)
; #pragma unroll
;       for (int i = 0; i < 16; i += 2) {
;         const int row = wm * 64 + mt * 32 + (i & 3) + 8 * (i >> 2) + 4 * h8;
;         const unsigned pr = pk2(acc[mt][nt][i], acc[mt][nt][i + 1]);
;         Cs[row * CSS + wn * 128 + nt * 32 + r] = (bfr)(pr & 0xffffu);
;         Cs[(row + 1) * CSS + wn * 128 + nt * 32 + r] = (bfr)(pr >> 16);
;       }
.Lgm_P4_loop:
	s_and_b32 s40, s39, 0x18000
	s_add_i32 s40, s38, s40
	s_waitcnt vmcnt(4)
	v_lshl_add_u64 v[176:177], v[140:141], 0, v[130:131]
	v_lshl_add_u64 v[178:179], v[136:137], 0, v[130:131]
	s_mov_b32 m0, s40
	s_barrier
	s_add_i32 s41, s39, 0xfffe8000
	s_and_b32 s41, s41, 0x18000
	s_add_i32 s42, s41, s36
	s_or_b32 s41, s41, s37
	v_add_u32_e32 v246, s42, v146
	v_add_u32_e32 v247, s41, v146
	s_waitcnt lgkmcnt(4)
	v_mfma_f32_32x32x16_bf16 v[114:129], v[196:199], v[204:207], v[114:129]
	global_load_lds_dwordx4 v[176:177], off
	s_add_i32 m0, s40, 0x4000
	ds_read_b128 v[220:223], v246
	s_waitcnt lgkmcnt(4)
	v_mfma_f32_32x32x16_bf16 v[50:65], v[200:203], v[204:207], v[50:65]
	v_lshl_add_u64 v[180:181], v[142:143], 0, v[130:131]
	global_load_lds_dwordx4 v[178:179], off
	s_add_i32 m0, s40, 0x400
	ds_read_b128 v[228:231], v247 offset:16384
	s_waitcnt lgkmcnt(4)
	v_mfma_f32_32x32x16_bf16 v[98:113], v[196:199], v[208:211], v[98:113]
	v_lshl_add_u64 v[182:183], v[138:139], 0, v[130:131]
	global_load_lds_dwordx4 v[180:181], off
	s_add_i32 m0, s40, 0x4400
	ds_read_b128 v[224:227], v246 offset:2048
	v_mfma_f32_32x32x16_bf16 v[34:49], v[200:203], v[208:211], v[34:49]
	ds_read_b128 v[232:235], v247 offset:18432
	global_load_lds_dwordx4 v[182:183], off
	s_waitcnt lgkmcnt(5)
	v_mfma_f32_32x32x16_bf16 v[82:97], v[196:199], v[212:215], v[82:97]
	ds_read_b128 v[236:239], v247 offset:20480
	v_lshl_add_u64 v[136:137], v[136:137], 0, s[18:19]
	v_lshl_add_u64 v[138:139], v[138:139], 0, s[18:19]
	v_mfma_f32_32x32x16_bf16 v[18:33], v[200:203], v[212:215], v[18:33]
	ds_read_b128 v[240:243], v247 offset:22528
	v_lshl_add_u64 v[140:141], v[140:141], 0, 64
	v_lshl_add_u64 v[142:143], v[142:143], 0, 64
	s_waitcnt lgkmcnt(6)
	v_mfma_f32_32x32x16_bf16 v[66:81], v[196:199], v[216:219], v[66:81]
	s_add_i32 s41, s39, 0xffff0000
	s_and_b32 s41, s41, 0x18000
	s_add_i32 s42, s41, s36
	v_mfma_f32_32x32x16_bf16 v[2:17], v[200:203], v[216:219], v[2:17]
	s_or_b32 s41, s41, s37
	v_add_u32_e32 v244, s42, v145
	v_add_u32_e32 v245, s41, v145
	s_waitcnt lgkmcnt(4)
	v_mfma_f32_32x32x16_bf16 v[114:129], v[220:223], v[228:231], v[114:129]
	ds_read_b128 v[196:199], v244
	s_waitcnt lgkmcnt(4)
	v_mfma_f32_32x32x16_bf16 v[50:65], v[224:227], v[228:231], v[50:65]
	ds_read_b128 v[204:207], v245 offset:16384
	s_waitcnt lgkmcnt(4)
	v_mfma_f32_32x32x16_bf16 v[98:113], v[220:223], v[232:235], v[98:113]
	ds_read_b128 v[200:203], v244 offset:2048
	v_mfma_f32_32x32x16_bf16 v[34:49], v[224:227], v[232:235], v[34:49]
	ds_read_b128 v[208:211], v245 offset:18432
	s_waitcnt lgkmcnt(5)
	v_mfma_f32_32x32x16_bf16 v[82:97], v[220:223], v[236:239], v[82:97]
	ds_read_b128 v[212:215], v245 offset:20480
	v_mfma_f32_32x32x16_bf16 v[18:33], v[224:227], v[236:239], v[18:33]
	ds_read_b128 v[216:219], v245 offset:22528
	s_waitcnt lgkmcnt(6)
	v_mfma_f32_32x32x16_bf16 v[66:81], v[220:223], v[240:243], v[66:81]
	s_add_i32 s39, s39, 0x8000
	v_mfma_f32_32x32x16_bf16 v[2:17], v[224:227], v[240:243], v[2:17]
	s_cmp_lg_u32 s39, 0x100000
	s_cbranch_scc1 .Lgm_P4_loop
	s_waitcnt vmcnt(8)
	v_add_u32_e32 v175, s37, v146
	s_waitcnt lgkmcnt(0)
	s_barrier
	ds_read_b128 v[136:139], v175 offset:55296
	ds_read_b128 v[140:143], v175 offset:53248
	ds_read_b128 v[176:179], v175 offset:51200
	ds_read_b128 v[180:183], v175 offset:49152
	v_add_u32_e32 v175, s36, v146
	ds_read_b128 v[184:187], v175 offset:34816
	ds_read_b128 v[188:191], v175 offset:32768
	v_add_u32_e32 v175, s37, v145
	ds_read_b128 v[192:195], v175 offset:55296
	ds_read_b128 v[196:199], v175 offset:53248
	ds_read_b128 v[200:203], v175 offset:51200
	ds_read_b128 v[204:207], v175 offset:49152
	v_add_u32_e32 v175, s36, v145
	ds_read_b128 v[208:211], v175 offset:34816
	ds_read_b128 v[212:215], v175 offset:32768
	s_waitcnt lgkmcnt(0)
	v_mfma_f32_32x32x16_bf16 v[114:129], v[212:215], v[204:207], v[114:129]
	s_or_b32 s40, s37, 0x14000
	s_waitcnt vmcnt(4)
	v_add_u32_e32 v175, s40, v146
	s_add_i32 s41, s36, 0x10000
	s_waitcnt lgkmcnt(0)
	s_barrier
	s_add_i32 s38, s24, 0xffff0000
	v_mfma_f32_32x32x16_bf16 v[50:65], v[208:211], v[204:207], v[50:65]
	s_lshr_b32 s38, s38, 14
	s_lshr_b32 s39, s35, 4
	s_add_i32 s27, s27, s28
	s_add_i32 s38, s38, 16
	s_cmpk_lt_i32 s35, 0x100
	s_cselect_b32 s35, s39, s38
	s_or_b32 s37, s37, 0x1c000
	v_mfma_f32_32x32x16_bf16 v[98:113], v[212:215], v[200:203], v[98:113]
	s_add_i32 s36, s36, 0x18000
	v_add_u32_e32 v172, s29, v172
	v_add_u32_e32 v173, s29, v173
	v_mfma_f32_32x32x16_bf16 v[34:49], v[208:211], v[200:203], v[34:49]
	v_mfma_f32_32x32x16_bf16 v[82:97], v[212:215], v[196:199], v[82:97]
	v_mfma_f32_32x32x16_bf16 v[18:33], v[208:211], v[196:199], v[18:33]
	v_mfma_f32_32x32x16_bf16 v[66:81], v[212:215], v[192:195], v[66:81]
	v_mfma_f32_32x32x16_bf16 v[2:17], v[208:211], v[192:195], v[2:17]
	v_mfma_f32_32x32x16_bf16 v[114:129], v[188:191], v[180:183], v[114:129]
	v_mfma_f32_32x32x16_bf16 v[50:65], v[184:187], v[180:183], v[50:65]
	v_mfma_f32_32x32x16_bf16 v[98:113], v[188:191], v[176:179], v[98:113]
	v_mfma_f32_32x32x16_bf16 v[34:49], v[184:187], v[176:179], v[34:49]
	v_mfma_f32_32x32x16_bf16 v[82:97], v[188:191], v[140:143], v[82:97]
	v_mfma_f32_32x32x16_bf16 v[18:33], v[184:187], v[140:143], v[18:33]
	v_mfma_f32_32x32x16_bf16 v[66:81], v[188:191], v[136:139], v[66:81]
	v_mfma_f32_32x32x16_bf16 v[2:17], v[184:187], v[136:139], v[2:17]
	ds_read_b128 v[136:139], v175 offset:6144
	ds_read_b128 v[140:143], v175 offset:4096
	ds_read_b128 v[176:179], v175 offset:2048
	ds_read_b128 v[180:183], v175
	v_add_u32_e32 v175, s41, v146
	ds_read_b128 v[184:187], v175 offset:2048
	ds_read_b128 v[188:191], v175
	v_add_u32_e32 v175, s40, v145
	ds_read_b128 v[192:195], v175 offset:6144
	ds_read_b128 v[196:199], v175 offset:4096
	ds_read_b128 v[200:203], v175 offset:2048
	ds_read_b128 v[204:207], v175
	v_add_u32_e32 v175, s41, v145
	ds_read_b128 v[208:211], v175 offset:2048
	ds_read_b128 v[212:215], v175
	s_waitcnt lgkmcnt(0)
	v_mfma_f32_32x32x16_bf16 v[114:129], v[212:215], v[204:207], v[114:129]
	s_waitcnt vmcnt(0)
	v_add_u32_e32 v175, s37, v146
	s_waitcnt lgkmcnt(0)
	s_barrier
; #define MFMA(a, b, c) __builtin_amdgcn_mfma_f32_32x32x16_bf16((a), (b), (c), 0, 0, 0)
; DI unsigned pk2(float a, float b) { fl2_t f = {a, b}; bf2_t r = __builtin_convertvector(f, bf2_t); return __builtin_bit_cast(unsigned, r); }
; #define WAIT_V(n) asm volatile("s_waitcnt vmcnt(%0)" ::"n"(n) : "memory")
; #define RAW_BARRIER() do { asm volatile("s_waitcnt lgkmcnt(0)" ::: "memory"); __builtin_amdgcn_s_barrier(); } while (0)
; template <typename FA, typename FB, typename FE>
; DI void gemm_tile(char* lds, int K, int astride, int bstride, FA arow, FB brow, FE epi) {
;     ...
;   for (int kt = 0; kt < nk; ++kt) {
;     if (kt + 2 < nk) WAIT_V(8); else if (kt + 1 < nk) WAIT_V(4); else WAIT_V(0);
;     RAW_BARRIER();
;     if (kt + 3 < nk) stage((kt + 3) & 3, kt + 3);
;     const char* sa = lds + (kt & 3) * 32768 + wm * 4096;
;     const char* sb = lds + (kt & 3) * 32768 + 16384 + wn * 8192;
; #pragma unroll
;     for (int ks = 0; ks < 2; ++ks) {
;       bf16x8 a0 = *(const bf16x8*)(sa + foff[ks]), a1 = *(const bf16x8*)(sa + 2048 + foff[ks]);
; #pragma unroll
;       for (int nt = 0; nt < 4; ++nt) {
;         bf16x8 bb = *(const bf16x8*)(sb + nt * 2048 + foff[ks]);
;         acc[0][nt] = MFMA(a0, bb, acc[0][nt]);
;         acc[1][nt] = MFMA(a1, bb, acc[1][nt]);
;       }
;     }
;   }
;   RAW_BARRIER();
;   bfr* Cs = (bfr*)lds;
; #pragma unroll
;   for (int mt = 0; mt < 2; ++mt)
; #pragma unroll
;     for (int nt = 0; nt < 4; ++nt)
; #pragma unroll
;       for (int i = 0; i < 16; i += 2) {
;         const int row = wm * 64 + mt * 32 + (i & 3) + 8 * (i >> 2) + 4 * h8;
;         const unsigned pr = pk2(acc[mt][nt][i], acc[mt][nt][i + 1]);
;         Cs[row * CSS + wn * 128 + nt * 32 + r] = (bfr)(pr & 0xffffu);
;         Cs[(row + 1) * CSS + wn * 128 + nt * 32 + r] = (bfr)(pr >> 16);
;       }
	v_mfma_f32_32x32x16_bf16 v[50:65], v[208:211], v[204:207], v[50:65]
	v_mfma_f32_32x32x16_bf16 v[98:113], v[212:215], v[200:203], v[98:113]
	v_mfma_f32_32x32x16_bf16 v[34:49], v[208:211], v[200:203], v[34:49]
	v_mfma_f32_32x32x16_bf16 v[82:97], v[212:215], v[196:199], v[82:97]
	v_mfma_f32_32x32x16_bf16 v[18:33], v[208:211], v[196:199], v[18:33]
	v_mfma_f32_32x32x16_bf16 v[66:81], v[212:215], v[192:195], v[66:81]
	v_mfma_f32_32x32x16_bf16 v[2:17], v[208:211], v[192:195], v[2:17]
	v_mfma_f32_32x32x16_bf16 v[114:129], v[188:191], v[180:183], v[114:129]
	v_mfma_f32_32x32x16_bf16 v[50:65], v[184:187], v[180:183], v[50:65]
	v_mfma_f32_32x32x16_bf16 v[98:113], v[188:191], v[176:179], v[98:113]
	v_mfma_f32_32x32x16_bf16 v[34:49], v[184:187], v[176:179], v[34:49]
	v_mfma_f32_32x32x16_bf16 v[82:97], v[188:191], v[140:143], v[82:97]
	v_mfma_f32_32x32x16_bf16 v[18:33], v[184:187], v[140:143], v[18:33]
	v_mfma_f32_32x32x16_bf16 v[66:81], v[188:191], v[136:139], v[66:81]
	v_mfma_f32_32x32x16_bf16 v[2:17], v[184:187], v[136:139], v[2:17]
	ds_read_b128 v[136:139], v175 offset:6144
	ds_read_b128 v[140:143], v175 offset:4096
	ds_read_b128 v[176:179], v175 offset:2048
	ds_read_b128 v[180:183], v175
	v_add_u32_e32 v175, s36, v146
	ds_read_b128 v[184:187], v175 offset:2048
	ds_read_b128 v[188:191], v175
	v_add_u32_e32 v175, s37, v145
	ds_read_b128 v[192:195], v175 offset:6144
	ds_read_b128 v[196:199], v175 offset:4096
	ds_read_b128 v[200:203], v175 offset:2048
	ds_read_b128 v[204:207], v175
	v_add_u32_e32 v175, s36, v145
	ds_read_b128 v[208:211], v175 offset:2048
	ds_read_b128 v[212:215], v175
	s_waitcnt lgkmcnt(0)
	v_mfma_f32_32x32x16_bf16 v[114:129], v[212:215], v[204:207], v[114:129]
	s_waitcnt lgkmcnt(0)
	s_barrier
	v_mfma_f32_32x32x16_bf16 v[98:113], v[212:215], v[200:203], v[98:113]
	v_mfma_f32_32x32x16_bf16 v[66:81], v[212:215], v[192:195], v[66:81]
	v_mfma_f32_32x32x16_bf16 v[2:17], v[208:211], v[192:195], v[2:17]
	v_mfma_f32_32x32x16_bf16 v[114:129], v[188:191], v[180:183], v[114:129]
	v_mfma_f32_32x32x16_bf16 v[82:97], v[212:215], v[196:199], v[82:97]
	v_mfma_f32_32x32x16_bf16 v[98:113], v[188:191], v[176:179], v[98:113]
	v_mfma_f32_32x32x16_bf16 v[66:81], v[188:191], v[136:139], v[66:81]
	s_nop 10
	v_cvt_pk_bf16_f32 v98, v98, v99
	v_mfma_f32_32x32x16_bf16 v[2:17], v[184:187], v[136:139], v[2:17]
	v_lshl_or_b32 v136, s34, 6, v147
	v_cvt_pk_bf16_f32 v137, v114, v115
	v_lshl_or_b32 v114, s33, 8, v171
	v_mad_u64_u32 v[114:115], s[36:37], v136, s31, v[114:115]
	v_cvt_pk_bf16_f32 v115, v116, v117
	ds_write_b16 v114, v137
	ds_write_b16_d16_hi v114, v137 offset:528
	ds_write_b16 v114, v115 offset:1056
	ds_write_b16_d16_hi v114, v115 offset:1584
	v_cvt_pk_bf16_f32 v115, v118, v119
	ds_write_b16 v114, v115 offset:4224
	ds_write_b16_d16_hi v114, v115 offset:4752
	v_cvt_pk_bf16_f32 v115, v120, v121
	ds_write_b16 v114, v115 offset:5280
	ds_write_b16_d16_hi v114, v115 offset:5808
	v_cvt_pk_bf16_f32 v115, v122, v123
	ds_write_b16 v114, v115 offset:8448
	ds_write_b16_d16_hi v114, v115 offset:8976
	v_cvt_pk_bf16_f32 v115, v124, v125
	v_mfma_f32_32x32x16_bf16 v[82:97], v[188:191], v[140:143], v[82:97]
	ds_write_b16 v114, v115 offset:9504
	ds_write_b16_d16_hi v114, v115 offset:10032
	v_cvt_pk_bf16_f32 v115, v126, v127
	ds_write_b16 v114, v115 offset:12672
	ds_write_b16_d16_hi v114, v115 offset:13200
	v_cvt_pk_bf16_f32 v115, v128, v129
	ds_write_b16 v114, v115 offset:13728
	ds_write_b16_d16_hi v114, v115 offset:14256
	ds_write_b16 v114, v98 offset:64
	ds_write_b16_d16_hi v114, v98 offset:592
	v_cvt_pk_bf16_f32 v98, v100, v101
	ds_write_b16 v114, v98 offset:1120
	ds_write_b16_d16_hi v114, v98 offset:1648
	v_cvt_pk_bf16_f32 v98, v102, v103
	ds_write_b16 v114, v98 offset:4288
	ds_write_b16_d16_hi v114, v98 offset:4816
	v_cvt_pk_bf16_f32 v98, v104, v105
	ds_write_b16 v114, v98 offset:5344
	ds_write_b16_d16_hi v114, v98 offset:5872
	v_cvt_pk_bf16_f32 v98, v106, v107
	v_mfma_f32_32x32x16_bf16 v[50:65], v[208:211], v[204:207], v[50:65]
	ds_write_b16 v114, v98 offset:8512
	ds_write_b16_d16_hi v114, v98 offset:9040
	v_cvt_pk_bf16_f32 v98, v108, v109
	ds_write_b16 v114, v98 offset:9568
	ds_write_b16_d16_hi v114, v98 offset:10096
	v_cvt_pk_bf16_f32 v98, v110, v111
	ds_write_b16 v114, v98 offset:12736
	ds_write_b16_d16_hi v114, v98 offset:13264
	v_cvt_pk_bf16_f32 v98, v112, v113
	v_cvt_pk_bf16_f32 v82, v82, v83
	ds_write_b16 v114, v98 offset:13792
	ds_write_b16_d16_hi v114, v98 offset:14320
	ds_write_b16 v114, v82 offset:128
	ds_write_b16_d16_hi v114, v82 offset:656
	v_cvt_pk_bf16_f32 v82, v84, v85
	ds_write_b16 v114, v82 offset:1184
	ds_write_b16_d16_hi v114, v82 offset:1712
	v_cvt_pk_bf16_f32 v82, v86, v87
	ds_write_b16 v114, v82 offset:4352
	ds_write_b16_d16_hi v114, v82 offset:4880
	v_cvt_pk_bf16_f32 v82, v88, v89
	ds_write_b16 v114, v82 offset:5408
	ds_write_b16_d16_hi v114, v82 offset:5936
	v_cvt_pk_bf16_f32 v82, v90, v91
	v_mfma_f32_32x32x16_bf16 v[34:49], v[208:211], v[200:203], v[34:49]
	ds_write_b16 v114, v82 offset:8576
	ds_write_b16_d16_hi v114, v82 offset:9104
	v_cvt_pk_bf16_f32 v82, v92, v93
	ds_write_b16 v114, v82 offset:9632
	ds_write_b16_d16_hi v114, v82 offset:10160
	v_cvt_pk_bf16_f32 v82, v94, v95
	ds_write_b16 v114, v82 offset:12800
	ds_write_b16_d16_hi v114, v82 offset:13328
	v_cvt_pk_bf16_f32 v82, v96, v97
	v_cvt_pk_bf16_f32 v66, v66, v67
	v_mfma_f32_32x32x16_bf16 v[50:65], v[184:187], v[180:183], v[50:65]
	ds_write_b16 v114, v82 offset:13856
	ds_write_b16_d16_hi v114, v82 offset:14384
	ds_write_b16 v114, v66 offset:192
	ds_write_b16_d16_hi v114, v66 offset:720
	v_cvt_pk_bf16_f32 v66, v68, v69
	ds_write_b16 v114, v66 offset:1248
	ds_write_b16_d16_hi v114, v66 offset:1776
; DI unsigned pk2(float a, float b) { fl2_t f = {a, b}; bf2_t r = __builtin_convertvector(f, bf2_t); return __builtin_bit_cast(unsigned, r); }
; template <typename FA, typename FB, typename FE>
; DI void gemm_tile(char* lds, int K, int astride, int bstride, FA arow, FB brow, FE epi) {
;     ...
; #pragma unroll
;   for (int mt = 0; mt < 2; ++mt)
; #pragma unroll
;     for (int nt = 0; nt < 4; ++nt)
; #pragma unroll
;       for (int i = 0; i < 16; i += 2) {
;         const int row = wm * 64 + mt * 32 + (i & 3) + 8 * (i >> 2) + 4 * h8;
;         const unsigned pr = pk2(acc[mt][nt][i], acc[mt][nt][i + 1]);
;         Cs[row * CSS + wn * 128 + nt * 32 + r] = (bfr)(pr & 0xffffu);
;         Cs[(row + 1) * CSS + wn * 128 + nt * 32 + r] = (bfr)(pr >> 16);
;       }
;   __syncthreads();
; DI void phase4(const Params& p, char* lds) {
;     ...
;       const int c4 = (tid & 31) * 4, col = nt2 * 256 + ch * 128 + c4, t0h = t0 + half * 128;
;       const float4 g1 = *(const float4*)(mod + br * 6144 + 2 * 1024 + col);
;       float4 xv[16];
; #pragma unroll
;       for (int ps = 0; ps < 16; ++ps) xv[ps] = *(const float4*)(xrow(p, t0h + ps * 8 + (tid >> 5)) + col);
	v_cvt_pk_bf16_f32 v66, v70, v71
	ds_write_b16 v114, v66 offset:4416
	ds_write_b16_d16_hi v114, v66 offset:4944
	v_cvt_pk_bf16_f32 v66, v72, v73
	ds_write_b16 v114, v66 offset:5472
	ds_write_b16_d16_hi v114, v66 offset:6000
	v_cvt_pk_bf16_f32 v66, v74, v75
	v_mfma_f32_32x32x16_bf16 v[18:33], v[208:211], v[196:199], v[18:33]
	ds_write_b16 v114, v66 offset:8640
	ds_write_b16_d16_hi v114, v66 offset:9168
	v_cvt_pk_bf16_f32 v66, v76, v77
	ds_write_b16 v114, v66 offset:9696
	ds_write_b16_d16_hi v114, v66 offset:10224
	v_cvt_pk_bf16_f32 v66, v78, v79
	ds_write_b16 v114, v66 offset:12864
	ds_write_b16_d16_hi v114, v66 offset:13392
	v_cvt_pk_bf16_f32 v66, v80, v81
	v_cvt_pk_bf16_f32 v50, v50, v51
	v_mfma_f32_32x32x16_bf16 v[34:49], v[184:187], v[176:179], v[34:49]
	ds_write_b16 v114, v66 offset:13920
	ds_write_b16_d16_hi v114, v66 offset:14448
	ds_write_b16 v114, v50 offset:16896
	ds_write_b16_d16_hi v114, v50 offset:17424
	v_cvt_pk_bf16_f32 v50, v52, v53
	ds_write_b16 v114, v50 offset:17952
	ds_write_b16_d16_hi v114, v50 offset:18480
	v_cvt_pk_bf16_f32 v50, v54, v55
	ds_write_b16 v114, v50 offset:21120
	ds_write_b16_d16_hi v114, v50 offset:21648
	v_cvt_pk_bf16_f32 v50, v56, v57
	ds_write_b16 v114, v50 offset:22176
	ds_write_b16_d16_hi v114, v50 offset:22704
	v_cvt_pk_bf16_f32 v50, v58, v59
	ds_write_b16 v114, v50 offset:25344
	ds_write_b16_d16_hi v114, v50 offset:25872
	v_cvt_pk_bf16_f32 v50, v60, v61
	v_mfma_f32_32x32x16_bf16 v[18:33], v[184:187], v[140:143], v[18:33]
	ds_write_b16 v114, v50 offset:26400
	ds_write_b16_d16_hi v114, v50 offset:26928
	v_cvt_pk_bf16_f32 v50, v62, v63
	ds_write_b16 v114, v50 offset:29568
	ds_write_b16_d16_hi v114, v50 offset:30096
	v_cvt_pk_bf16_f32 v50, v64, v65
	v_cvt_pk_bf16_f32 v34, v34, v35
	ds_write_b16 v114, v50 offset:30624
	ds_write_b16_d16_hi v114, v50 offset:31152
	ds_write_b16 v114, v34 offset:16960
	ds_write_b16_d16_hi v114, v34 offset:17488
	v_cvt_pk_bf16_f32 v34, v36, v37
	ds_write_b16 v114, v34 offset:18016
	ds_write_b16_d16_hi v114, v34 offset:18544
	v_cvt_pk_bf16_f32 v34, v38, v39
	ds_write_b16 v114, v34 offset:21184
	ds_write_b16_d16_hi v114, v34 offset:21712
	v_cvt_pk_bf16_f32 v34, v40, v41
	ds_write_b16 v114, v34 offset:22240
	ds_write_b16_d16_hi v114, v34 offset:22768
	v_cvt_pk_bf16_f32 v34, v42, v43
	ds_write_b16 v114, v34 offset:25408
	ds_write_b16_d16_hi v114, v34 offset:25936
	v_cvt_pk_bf16_f32 v34, v44, v45
	ds_write_b16 v114, v34 offset:26464
	ds_write_b16_d16_hi v114, v34 offset:26992
	v_cvt_pk_bf16_f32 v34, v46, v47
	ds_write_b16 v114, v34 offset:29632
	ds_write_b16_d16_hi v114, v34 offset:30160
	v_cvt_pk_bf16_f32 v34, v48, v49
	v_cvt_pk_bf16_f32 v18, v18, v19
	ds_write_b16 v114, v34 offset:30688
	ds_write_b16_d16_hi v114, v34 offset:31216
	ds_write_b16 v114, v18 offset:17024
	ds_write_b16_d16_hi v114, v18 offset:17552
	v_cvt_pk_bf16_f32 v18, v20, v21
	ds_write_b16 v114, v18 offset:18080
	ds_write_b16_d16_hi v114, v18 offset:18608
	v_cvt_pk_bf16_f32 v18, v22, v23
	ds_write_b16 v114, v18 offset:21248
	ds_write_b16_d16_hi v114, v18 offset:21776
	v_cvt_pk_bf16_f32 v18, v24, v25
	ds_write_b16 v114, v18 offset:22304
	ds_write_b16_d16_hi v114, v18 offset:22832
	v_cvt_pk_bf16_f32 v18, v26, v27
	ds_write_b16 v114, v18 offset:25472
	ds_write_b16_d16_hi v114, v18 offset:26000
	v_cvt_pk_bf16_f32 v18, v28, v29
	ds_write_b16 v114, v18 offset:26528
	ds_write_b16_d16_hi v114, v18 offset:27056
	v_cvt_pk_bf16_f32 v18, v30, v31
	ds_write_b16 v114, v18 offset:29696
	ds_write_b16_d16_hi v114, v18 offset:30224
	v_cvt_pk_bf16_f32 v18, v32, v33
	v_cvt_pk_bf16_f32 v2, v2, v3
	ds_write_b16 v114, v18 offset:30752
	ds_write_b16_d16_hi v114, v18 offset:31280
	ds_write_b16 v114, v2 offset:17088
	ds_write_b16_d16_hi v114, v2 offset:17616
	v_cvt_pk_bf16_f32 v2, v4, v5
	ds_write_b16 v114, v2 offset:18144
	ds_write_b16_d16_hi v114, v2 offset:18672
	v_cvt_pk_bf16_f32 v2, v6, v7
	ds_write_b16 v114, v2 offset:21312
	ds_write_b16_d16_hi v114, v2 offset:21840
	v_cvt_pk_bf16_f32 v2, v8, v9
	ds_write_b16 v114, v2 offset:22368
	ds_write_b16_d16_hi v114, v2 offset:22896
	v_cvt_pk_bf16_f32 v2, v10, v11
	v_add_u32_e32 v10, s24, v148
	v_or_b32_e32 v4, v10, v150
	ds_write_b16 v114, v2 offset:25536
	ds_write_b16_d16_hi v114, v2 offset:26064
	v_cvt_pk_bf16_f32 v2, v12, v13
	v_cmp_gt_i32_e32 vcc, s30, v4
	v_add_u32_e32 v6, 0xffff0000, v4
	v_ashrrev_i32_e32 v5, 31, v4
	ds_write_b16 v114, v2 offset:26592
	ds_write_b16_d16_hi v114, v2 offset:27120
	v_cvt_pk_bf16_f32 v2, v14, v15
	v_or_b32_e32 v70, s25, v149
	v_cndmask_b32_e32 v7, 0, v5, vcc
	v_cndmask_b32_e32 v6, v6, v4, vcc
	v_mov_b32_e32 v11, s11
	v_mov_b32_e32 v12, s9
	v_mov_b32_e32 v13, s10
	v_mov_b32_e32 v14, s8
	ds_write_b16 v114, v2 offset:29760
	ds_write_b16_d16_hi v114, v2 offset:30288
	v_cvt_pk_bf16_f32 v2, v16, v17
	v_ashrrev_i32_e32 v71, 31, v70
	v_cndmask_b32_e32 v9, v11, v12, vcc
	v_cndmask_b32_e32 v8, v13, v14, vcc
	v_lshlrev_b64 v[6:7], 12, v[6:7]
	ds_write_b16 v114, v2 offset:30816
	ds_write_b16_d16_hi v114, v2 offset:31344
	v_lshlrev_b64 v[2:3], 2, v[70:71]
	v_lshl_add_u64 v[6:7], v[8:9], 0, v[6:7]
	v_lshl_add_u64 v[68:69], v[6:7], 0, v[2:3]
	v_or_b32_e32 v6, 8, v4
	v_cmp_gt_i32_e32 vcc, s30, v6
	v_add_u32_e32 v8, 0xffff0008, v4
	v_ashrrev_i32_e32 v7, 31, v6
	v_cndmask_b32_e32 v7, 0, v7, vcc
	v_cndmask_b32_e32 v6, v8, v6, vcc
	v_cndmask_b32_e32 v9, v11, v12, vcc
	v_cndmask_b32_e32 v8, v13, v14, vcc
	v_lshlrev_b64 v[6:7], 12, v[6:7]
	v_lshl_add_u64 v[6:7], v[8:9], 0, v[6:7]
	v_lshl_add_u64 v[74:75], v[6:7], 0, v[2:3]
	v_or_b32_e32 v6, 16, v4
	v_cmp_gt_i32_e32 vcc, s30, v6
	v_add_u32_e32 v8, 0xffff0010, v4
	v_ashrrev_i32_e32 v7, 31, v6
	v_cndmask_b32_e32 v7, 0, v7, vcc
; DI void phase4(const Params& p, char* lds) {
;     ...
;       const int c4 = (tid & 31) * 4, col = nt2 * 256 + ch * 128 + c4, t0h = t0 + half * 128;
;       const float4 g1 = *(const float4*)(mod + br * 6144 + 2 * 1024 + col);
;       float4 xv[16];
; #pragma unroll
;       for (int ps = 0; ps < 16; ++ps) xv[ps] = *(const float4*)(xrow(p, t0h + ps * 8 + (tid >> 5)) + col);
	v_cndmask_b32_e32 v6, v8, v6, vcc
	v_cndmask_b32_e32 v9, v11, v12, vcc
	v_cndmask_b32_e32 v8, v13, v14, vcc
	v_lshlrev_b64 v[6:7], 12, v[6:7]
	v_lshl_add_u64 v[6:7], v[8:9], 0, v[6:7]
	v_lshl_add_u64 v[78:79], v[6:7], 0, v[2:3]
	v_or_b32_e32 v6, 24, v4
	v_cmp_gt_i32_e32 vcc, s30, v6
	v_add_u32_e32 v8, 0xffff0018, v4
	v_ashrrev_i32_e32 v7, 31, v6
	v_cndmask_b32_e32 v7, 0, v7, vcc
	v_cndmask_b32_e32 v6, v8, v6, vcc
	v_cndmask_b32_e32 v9, v11, v12, vcc
	v_cndmask_b32_e32 v8, v13, v14, vcc
	v_lshlrev_b64 v[6:7], 12, v[6:7]
	v_lshl_add_u64 v[6:7], v[8:9], 0, v[6:7]
	v_lshl_add_u64 v[84:85], v[6:7], 0, v[2:3]
	v_or_b32_e32 v6, 32, v4
	v_cmp_gt_i32_e32 vcc, s30, v6
	v_add_u32_e32 v8, 0xffff0020, v4
	v_ashrrev_i32_e32 v7, 31, v6
	v_cndmask_b32_e32 v7, 0, v7, vcc
	v_cndmask_b32_e32 v6, v8, v6, vcc
	v_cndmask_b32_e32 v9, v11, v12, vcc
	v_cndmask_b32_e32 v8, v13, v14, vcc
	v_lshlrev_b64 v[6:7], 12, v[6:7]
	v_lshl_add_u64 v[6:7], v[8:9], 0, v[6:7]
	v_lshl_add_u64 v[90:91], v[6:7], 0, v[2:3]
	v_or_b32_e32 v6, 40, v4
	v_cmp_gt_i32_e32 vcc, s30, v6
	v_add_u32_e32 v8, 0xffff0028, v4
	v_ashrrev_i32_e32 v7, 31, v6
	v_cndmask_b32_e32 v7, 0, v7, vcc
	v_cndmask_b32_e32 v6, v8, v6, vcc
	v_cndmask_b32_e32 v9, v11, v12, vcc
	v_cndmask_b32_e32 v8, v13, v14, vcc
	v_lshlrev_b64 v[6:7], 12, v[6:7]
	v_lshl_add_u64 v[6:7], v[8:9], 0, v[6:7]
	v_lshl_add_u64 v[94:95], v[6:7], 0, v[2:3]
	v_or_b32_e32 v6, 48, v4
	v_cmp_gt_i32_e32 vcc, s30, v6
	v_add_u32_e32 v8, 0xffff0030, v4
	v_ashrrev_i32_e32 v7, 31, v6
	v_cndmask_b32_e32 v7, 0, v7, vcc
	v_cndmask_b32_e32 v6, v8, v6, vcc
	v_cndmask_b32_e32 v9, v11, v12, vcc
	v_cndmask_b32_e32 v8, v13, v14, vcc
	v_lshlrev_b64 v[6:7], 12, v[6:7]
	v_lshl_add_u64 v[6:7], v[8:9], 0, v[6:7]
	v_lshl_add_u64 v[100:101], v[6:7], 0, v[2:3]
	v_or_b32_e32 v6, 56, v4
	v_cmp_gt_i32_e32 vcc, s30, v6
	v_add_u32_e32 v8, 0xffff0038, v4
	v_ashrrev_i32_e32 v7, 31, v6
	v_cndmask_b32_e32 v7, 0, v7, vcc
	v_cndmask_b32_e32 v6, v8, v6, vcc
	v_cndmask_b32_e32 v9, v11, v12, vcc
	v_cndmask_b32_e32 v8, v13, v14, vcc
	v_lshlrev_b64 v[6:7], 12, v[6:7]
	v_lshl_add_u64 v[6:7], v[8:9], 0, v[6:7]
	v_lshl_add_u64 v[106:107], v[6:7], 0, v[2:3]
	v_or_b32_e32 v6, 64, v4
	v_cmp_gt_i32_e32 vcc, s30, v6
	v_add_u32_e32 v8, 0xffff0040, v4
	v_ashrrev_i32_e32 v7, 31, v6
	v_cndmask_b32_e32 v7, 0, v7, vcc
	v_cndmask_b32_e32 v6, v8, v6, vcc
	v_cndmask_b32_e32 v9, v11, v12, vcc
	v_cndmask_b32_e32 v8, v13, v14, vcc
	v_lshlrev_b64 v[6:7], 12, v[6:7]
	v_lshl_add_u64 v[6:7], v[8:9], 0, v[6:7]
	v_lshl_add_u64 v[110:111], v[6:7], 0, v[2:3]
	v_or_b32_e32 v6, 0x48, v4
	v_cmp_gt_i32_e32 vcc, s30, v6
	v_add_u32_e32 v8, 0xffff0048, v4
	v_ashrrev_i32_e32 v7, 31, v6
	v_cndmask_b32_e32 v7, 0, v7, vcc
	v_cndmask_b32_e32 v6, v8, v6, vcc
	v_cndmask_b32_e32 v9, v11, v12, vcc
	v_cndmask_b32_e32 v8, v13, v14, vcc
	v_lshlrev_b64 v[6:7], 12, v[6:7]
	v_lshl_add_u64 v[6:7], v[8:9], 0, v[6:7]
	v_lshl_add_u64 v[114:115], v[6:7], 0, v[2:3]
	v_or_b32_e32 v6, 0x50, v4
	v_cmp_gt_i32_e32 vcc, s30, v6
	v_add_u32_e32 v8, 0xffff0050, v4
	v_ashrrev_i32_e32 v7, 31, v6
	v_cndmask_b32_e32 v7, 0, v7, vcc
	v_cndmask_b32_e32 v6, v8, v6, vcc
	v_cndmask_b32_e32 v9, v11, v12, vcc
	v_cndmask_b32_e32 v8, v13, v14, vcc
	v_lshlrev_b64 v[6:7], 12, v[6:7]
	v_lshl_add_u64 v[6:7], v[8:9], 0, v[6:7]
	v_lshl_add_u64 v[116:117], v[6:7], 0, v[2:3]
	v_or_b32_e32 v6, 0x58, v4
	v_cmp_gt_i32_e32 vcc, s30, v6
	v_add_u32_e32 v8, 0xffff0058, v4
	v_ashrrev_i32_e32 v7, 31, v6
	v_cndmask_b32_e32 v7, 0, v7, vcc
	v_cndmask_b32_e32 v6, v8, v6, vcc
	v_cndmask_b32_e32 v9, v11, v12, vcc
	v_cndmask_b32_e32 v8, v13, v14, vcc
	v_lshlrev_b64 v[6:7], 12, v[6:7]
	v_lshl_add_u64 v[6:7], v[8:9], 0, v[6:7]
	v_lshl_add_u64 v[118:119], v[6:7], 0, v[2:3]
	v_or_b32_e32 v6, 0x60, v4
	v_cmp_gt_i32_e32 vcc, s30, v6
	v_add_u32_e32 v8, 0xffff0060, v4
	v_ashrrev_i32_e32 v7, 31, v6
	v_cndmask_b32_e32 v7, 0, v7, vcc
	v_cndmask_b32_e32 v6, v8, v6, vcc
	v_cndmask_b32_e32 v9, v11, v12, vcc
	v_cndmask_b32_e32 v8, v13, v14, vcc
	v_lshlrev_b64 v[6:7], 12, v[6:7]
	v_lshl_add_u64 v[6:7], v[8:9], 0, v[6:7]
	v_lshl_add_u64 v[120:121], v[6:7], 0, v[2:3]
	v_or_b32_e32 v6, 0x68, v4
	v_cmp_gt_i32_e32 vcc, s30, v6
	v_add_u32_e32 v8, 0xffff0068, v4
	v_ashrrev_i32_e32 v7, 31, v6
	v_cndmask_b32_e32 v7, 0, v7, vcc
	v_cndmask_b32_e32 v6, v8, v6, vcc
	v_cndmask_b32_e32 v9, v11, v12, vcc
	v_cndmask_b32_e32 v8, v13, v14, vcc
	v_lshlrev_b64 v[6:7], 12, v[6:7]
	v_lshl_add_u64 v[6:7], v[8:9], 0, v[6:7]
	v_lshl_add_u64 v[122:123], v[6:7], 0, v[2:3]
	v_or_b32_e32 v6, 0x70, v4
	v_cmp_gt_i32_e32 vcc, s30, v6
	v_add_u32_e32 v8, 0xffff0070, v4
	v_ashrrev_i32_e32 v7, 31, v6
	v_cndmask_b32_e32 v7, 0, v7, vcc
	v_cndmask_b32_e32 v6, v8, v6, vcc
	v_cndmask_b32_e32 v9, v11, v12, vcc
	v_cndmask_b32_e32 v8, v13, v14, vcc
	v_lshlrev_b64 v[6:7], 12, v[6:7]
	v_lshl_add_u64 v[6:7], v[8:9], 0, v[6:7]
	v_lshl_add_u64 v[124:125], v[6:7], 0, v[2:3]
	v_or_b32_e32 v6, 0x78, v4
	v_add_u32_e32 v8, 0xffff0078, v4
	v_lshlrev_b64 v[4:5], 12, v[4:5]
	v_lshl_add_u64 v[4:5], s[4:5], 0, v[4:5]
	v_lshl_add_u64 v[112:113], v[4:5], 0, v[2:3]
	v_or_b32_e32 v4, v10, v152
	v_ashrrev_i32_e32 v5, 31, v4
	v_lshlrev_b64 v[4:5], 12, v[4:5]
	v_lshl_add_u64 v[4:5], s[4:5], 0, v[4:5]
	v_lshl_add_u64 v[108:109], v[4:5], 0, v[2:3]
	v_or_b32_e32 v4, v10, v153
	v_ashrrev_i32_e32 v5, 31, v4
	v_lshlrev_b64 v[4:5], 12, v[4:5]
	v_lshl_add_u64 v[4:5], s[4:5], 0, v[4:5]
	v_lshl_add_u64 v[104:105], v[4:5], 0, v[2:3]
	v_or_b32_e32 v4, v10, v154
	v_ashrrev_i32_e32 v5, 31, v4
	v_lshlrev_b64 v[4:5], 12, v[4:5]
	v_lshl_add_u64 v[4:5], s[4:5], 0, v[4:5]
	v_lshl_add_u64 v[102:103], v[4:5], 0, v[2:3]
	v_or_b32_e32 v4, v10, v156
	v_ashrrev_i32_e32 v5, 31, v4
; DI void phase4(const Params& p, char* lds) {
;     ...
;       const bfr* Cs = Cs0 + half * 128 * CSS + ch * 128;
;       const int c4 = (tid & 31) * 4, col = nt2 * 256 + ch * 128 + c4, t0h = t0 + half * 128;
;       const float4 g1 = *(const float4*)(mod + br * 6144 + 2 * 1024 + col);
;       float4 xv[16];
; #pragma unroll
;       for (int ps = 0; ps < 16; ++ps) xv[ps] = *(const float4*)(xrow(p, t0h + ps * 8 + (tid >> 5)) + col);
;       asm volatile("" ::: "memory");
; #pragma unroll
;       for (int ps = 0; ps < 16; ++ps) {
;         const int row = ps * 8 + (tid >> 5), t = t0h + row;
;         float4 c = cs4(Cs, row, c4);
;         float4 o = make_float4(xv[ps].x + g1.x * c.x, xv[ps].y + g1.y * c.y, xv[ps].z + g1.z * c.z, xv[ps].w + g1.w * c.w);
;         *(float4*)(p.out + (size_t)t * D + col) = o;
;       }
	v_lshlrev_b64 v[4:5], 12, v[4:5]
	v_lshl_add_u64 v[4:5], s[4:5], 0, v[4:5]
	v_lshl_add_u64 v[98:99], v[4:5], 0, v[2:3]
	v_or_b32_e32 v4, v10, v157
	v_ashrrev_i32_e32 v5, 31, v4
	v_lshlrev_b64 v[4:5], 12, v[4:5]
	v_lshl_add_u64 v[4:5], s[4:5], 0, v[4:5]
	v_lshl_add_u64 v[96:97], v[4:5], 0, v[2:3]
	v_or_b32_e32 v4, v10, v158
	v_ashrrev_i32_e32 v5, 31, v4
	v_lshlrev_b64 v[4:5], 12, v[4:5]
	v_lshl_add_u64 v[4:5], s[4:5], 0, v[4:5]
	v_lshl_add_u64 v[92:93], v[4:5], 0, v[2:3]
	v_or_b32_e32 v4, v10, v159
	v_ashrrev_i32_e32 v5, 31, v4
	v_lshlrev_b64 v[4:5], 12, v[4:5]
	v_lshl_add_u64 v[4:5], s[4:5], 0, v[4:5]
	v_lshl_add_u64 v[88:89], v[4:5], 0, v[2:3]
	v_or_b32_e32 v4, v10, v161
	v_ashrrev_i32_e32 v5, 31, v4
	v_lshlrev_b64 v[4:5], 12, v[4:5]
	v_lshl_add_u64 v[4:5], s[4:5], 0, v[4:5]
	v_lshl_add_u64 v[86:87], v[4:5], 0, v[2:3]
	v_or_b32_e32 v4, v10, v162
	v_ashrrev_i32_e32 v5, 31, v4
	v_lshlrev_b64 v[4:5], 12, v[4:5]
	v_lshl_add_u64 v[4:5], s[4:5], 0, v[4:5]
	v_lshl_add_u64 v[82:83], v[4:5], 0, v[2:3]
	v_or_b32_e32 v4, v10, v163
	v_ashrrev_i32_e32 v5, 31, v4
	v_lshlrev_b64 v[4:5], 12, v[4:5]
	v_lshl_add_u64 v[4:5], s[4:5], 0, v[4:5]
	v_lshl_add_u64 v[80:81], v[4:5], 0, v[2:3]
	v_or_b32_e32 v4, v10, v164
	v_ashrrev_i32_e32 v5, 31, v4
	v_lshlrev_b64 v[4:5], 12, v[4:5]
	v_lshl_add_u64 v[4:5], s[4:5], 0, v[4:5]
	v_lshl_add_u64 v[76:77], v[4:5], 0, v[2:3]
	v_or_b32_e32 v4, v10, v166
	v_ashrrev_i32_e32 v5, 31, v4
	v_lshlrev_b64 v[4:5], 12, v[4:5]
	v_lshl_add_u64 v[4:5], s[4:5], 0, v[4:5]
	v_lshl_add_u64 v[72:73], v[4:5], 0, v[2:3]
	v_or_b32_e32 v4, v10, v167
	v_ashrrev_i32_e32 v5, 31, v4
	v_lshlrev_b64 v[4:5], 12, v[4:5]
	v_lshl_add_u64 v[4:5], s[4:5], 0, v[4:5]
	s_mul_i32 s24, s35, 0x1800
	v_lshl_add_u64 v[66:67], v[4:5], 0, v[2:3]
	v_or_b32_e32 v4, v10, v168
	s_ashr_i32 s25, s24, 31
	v_ashrrev_i32_e32 v5, 31, v4
	s_lshl_b64 s[24:25], s[24:25], 2
	v_lshlrev_b64 v[4:5], 12, v[4:5]
	s_add_u32 s24, s6, s24
	v_lshl_add_u64 v[4:5], s[4:5], 0, v[4:5]
	s_addc_u32 s25, s7, s25
	v_cmp_gt_i32_e32 vcc, s30, v6
	v_ashrrev_i32_e32 v7, 31, v6
	v_lshl_add_u64 v[64:65], v[4:5], 0, v[2:3]
	v_or_b32_e32 v4, v10, v169
	s_add_u32 s24, s24, 0x2000
	v_cndmask_b32_e32 v7, 0, v7, vcc
	v_cndmask_b32_e32 v6, v8, v6, vcc
	v_ashrrev_i32_e32 v5, 31, v4
	s_addc_u32 s25, s25, 0
	v_cndmask_b32_e32 v9, v11, v12, vcc
	v_cndmask_b32_e32 v8, v13, v14, vcc
	v_lshlrev_b64 v[6:7], 12, v[6:7]
	v_lshlrev_b64 v[4:5], 12, v[4:5]
	v_lshl_add_u64 v[22:23], s[24:25], 0, v[2:3]
	v_lshl_add_u64 v[6:7], v[8:9], 0, v[6:7]
	v_lshl_add_u64 v[4:5], s[4:5], 0, v[4:5]
	s_waitcnt vmcnt(0) lgkmcnt(0)
	s_barrier
	v_lshl_add_u64 v[126:127], v[6:7], 0, v[2:3]
	v_lshl_add_u64 v[62:63], v[4:5], 0, v[2:3]
	global_load_dwordx4 v[2:5], v[22:23], off
	global_load_dwordx4 v[6:9], v[126:127], off nt
	global_load_dwordx4 v[10:13], v[124:125], off nt
	global_load_dwordx4 v[14:17], v[122:123], off nt
	global_load_dwordx4 v[18:21], v[120:121], off nt
	s_nop 0
	global_load_dwordx4 v[22:25], v[118:119], off nt
	global_load_dwordx4 v[26:29], v[116:117], off nt
	global_load_dwordx4 v[30:33], v[114:115], off nt
	global_load_dwordx4 v[34:37], v[110:111], off nt
	global_load_dwordx4 v[38:41], v[106:107], off nt
	global_load_dwordx4 v[42:45], v[100:101], off nt
	global_load_dwordx4 v[46:49], v[94:95], off nt
	global_load_dwordx4 v[50:53], v[90:91], off nt
	global_load_dwordx4 v[54:57], v[84:85], off nt
	global_load_dwordx4 v[58:61], v[78:79], off nt
	global_load_dwordx4 v[136:139], v[74:75], off nt
	global_load_dwordx4 v[140:143], v[68:69], off nt
	ds_read_b64 v[128:129], v151
	s_cmp_lt_i32 s27, s26
	s_waitcnt lgkmcnt(0)
	v_lshlrev_b32_e32 v176, 16, v128
	v_and_b32_e32 v177, 0xffff0000, v128
	v_lshlrev_b32_e32 v128, 16, v129
	v_and_b32_e32 v129, 0xffff0000, v129
	s_waitcnt vmcnt(0)
	v_pk_fma_f32 v[142:143], v[4:5], v[128:129], v[142:143]
	ds_read_b64 v[128:129], v151 offset:4224
	v_pk_fma_f32 v[140:141], v[2:3], v[176:177], v[140:141]
	global_store_dwordx4 v[112:113], v[140:143], off
	s_waitcnt lgkmcnt(0)
	s_nop 0
	v_lshlrev_b32_e32 v140, 16, v128
	v_and_b32_e32 v141, 0xffff0000, v128
	v_lshlrev_b32_e32 v128, 16, v129
	v_and_b32_e32 v129, 0xffff0000, v129
	v_pk_fma_f32 v[138:139], v[4:5], v[128:129], v[138:139]
	ds_read_b64 v[128:129], v151 offset:8448
	v_pk_fma_f32 v[136:137], v[2:3], v[140:141], v[136:137]
	global_store_dwordx4 v[108:109], v[136:139], off
	s_waitcnt lgkmcnt(0)
	s_nop 0
	v_lshlrev_b32_e32 v136, 16, v128
	v_and_b32_e32 v137, 0xffff0000, v128
	v_lshlrev_b32_e32 v128, 16, v129
	v_and_b32_e32 v129, 0xffff0000, v129
	v_pk_fma_f32 v[58:59], v[2:3], v[136:137], v[58:59]
	v_pk_fma_f32 v[60:61], v[4:5], v[128:129], v[60:61]
	global_store_dwordx4 v[104:105], v[58:61], off
	ds_read_b64 v[58:59], v155
	s_waitcnt lgkmcnt(0)
	v_lshlrev_b32_e32 v60, 16, v58
	v_and_b32_e32 v61, 0xffff0000, v58
	v_lshlrev_b32_e32 v58, 16, v59
	v_and_b32_e32 v59, 0xffff0000, v59
	v_pk_fma_f32 v[54:55], v[2:3], v[60:61], v[54:55]
	v_pk_fma_f32 v[56:57], v[4:5], v[58:59], v[56:57]
	global_store_dwordx4 v[102:103], v[54:57], off
	ds_read_b64 v[54:55], v151 offset:16896
	s_waitcnt lgkmcnt(0)
	v_lshlrev_b32_e32 v56, 16, v54
	v_and_b32_e32 v57, 0xffff0000, v54
	v_lshlrev_b32_e32 v54, 16, v55
	v_and_b32_e32 v55, 0xffff0000, v55
	v_pk_fma_f32 v[50:51], v[2:3], v[56:57], v[50:51]
	v_pk_fma_f32 v[52:53], v[4:5], v[54:55], v[52:53]
	global_store_dwordx4 v[98:99], v[50:53], off
	ds_read_b64 v[50:51], v151 offset:21120
	s_waitcnt lgkmcnt(0)
	v_lshlrev_b32_e32 v52, 16, v50
	v_and_b32_e32 v53, 0xffff0000, v50
	v_lshlrev_b32_e32 v50, 16, v51
	v_and_b32_e32 v51, 0xffff0000, v51
	v_pk_fma_f32 v[46:47], v[2:3], v[52:53], v[46:47]
	v_pk_fma_f32 v[48:49], v[4:5], v[50:51], v[48:49]
	global_store_dwordx4 v[96:97], v[46:49], off
	ds_read_b64 v[46:47], v151 offset:25344
	s_waitcnt lgkmcnt(0)
; DI void phase4(const Params& p, char* lds) {
;     ...
;       const bfr* Cs = Cs0 + half * 128 * CSS + ch * 128;
;       const int c4 = (tid & 31) * 4, col = nt2 * 256 + ch * 128 + c4, t0h = t0 + half * 128;
;       const float4 g1 = *(const float4*)(mod + br * 6144 + 2 * 1024 + col);
;       float4 xv[16];
; #pragma unroll
;       for (int ps = 0; ps < 16; ++ps) xv[ps] = *(const float4*)(xrow(p, t0h + ps * 8 + (tid >> 5)) + col);
;       asm volatile("" ::: "memory");
; #pragma unroll
;       for (int ps = 0; ps < 16; ++ps) {
;         const int row = ps * 8 + (tid >> 5), t = t0h + row;
;         float4 c = cs4(Cs, row, c4);
;         float4 o = make_float4(xv[ps].x + g1.x * c.x, xv[ps].y + g1.y * c.y, xv[ps].z + g1.z * c.z, xv[ps].w + g1.w * c.w);
;         *(float4*)(p.out + (size_t)t * D + col) = o;
;       }
	v_lshlrev_b32_e32 v48, 16, v46
	v_and_b32_e32 v49, 0xffff0000, v46
	v_lshlrev_b32_e32 v46, 16, v47
	v_and_b32_e32 v47, 0xffff0000, v47
	v_pk_fma_f32 v[42:43], v[2:3], v[48:49], v[42:43]
	v_pk_fma_f32 v[44:45], v[4:5], v[46:47], v[44:45]
	global_store_dwordx4 v[92:93], v[42:45], off
	ds_read_b64 v[42:43], v160
	s_waitcnt lgkmcnt(0)
	v_lshlrev_b32_e32 v44, 16, v42
	v_and_b32_e32 v45, 0xffff0000, v42
	v_lshlrev_b32_e32 v42, 16, v43
	v_and_b32_e32 v43, 0xffff0000, v43
	v_pk_fma_f32 v[38:39], v[2:3], v[44:45], v[38:39]
	v_pk_fma_f32 v[40:41], v[4:5], v[42:43], v[40:41]
	global_store_dwordx4 v[88:89], v[38:41], off
	ds_read_b64 v[38:39], v151 offset:33792
	s_waitcnt lgkmcnt(0)
	v_lshlrev_b32_e32 v40, 16, v38
	v_and_b32_e32 v41, 0xffff0000, v38
	v_lshlrev_b32_e32 v38, 16, v39
	v_and_b32_e32 v39, 0xffff0000, v39
	v_pk_fma_f32 v[34:35], v[2:3], v[40:41], v[34:35]
	v_pk_fma_f32 v[36:37], v[4:5], v[38:39], v[36:37]
	global_store_dwordx4 v[86:87], v[34:37], off
	ds_read_b64 v[34:35], v151 offset:38016
	s_waitcnt lgkmcnt(0)
	v_lshlrev_b32_e32 v36, 16, v34
	v_and_b32_e32 v37, 0xffff0000, v34
	v_lshlrev_b32_e32 v34, 16, v35
	v_and_b32_e32 v35, 0xffff0000, v35
	v_pk_fma_f32 v[30:31], v[2:3], v[36:37], v[30:31]
	v_pk_fma_f32 v[32:33], v[4:5], v[34:35], v[32:33]
	global_store_dwordx4 v[82:83], v[30:33], off
	ds_read_b64 v[30:31], v151 offset:42240
	s_waitcnt lgkmcnt(0)
	v_lshlrev_b32_e32 v32, 16, v30
	v_and_b32_e32 v33, 0xffff0000, v30
	v_lshlrev_b32_e32 v30, 16, v31
	v_and_b32_e32 v31, 0xffff0000, v31
	v_pk_fma_f32 v[26:27], v[2:3], v[32:33], v[26:27]
	v_pk_fma_f32 v[28:29], v[4:5], v[30:31], v[28:29]
	global_store_dwordx4 v[80:81], v[26:29], off
	ds_read_b64 v[26:27], v165
	s_waitcnt lgkmcnt(0)
	v_lshlrev_b32_e32 v28, 16, v26
	v_and_b32_e32 v29, 0xffff0000, v26
	v_lshlrev_b32_e32 v26, 16, v27
	v_and_b32_e32 v27, 0xffff0000, v27
	v_pk_fma_f32 v[22:23], v[2:3], v[28:29], v[22:23]
	v_pk_fma_f32 v[24:25], v[4:5], v[26:27], v[24:25]
	global_store_dwordx4 v[76:77], v[22:25], off
	ds_read_b64 v[22:23], v151 offset:50688
	s_waitcnt lgkmcnt(0)
	v_lshlrev_b32_e32 v24, 16, v22
	v_and_b32_e32 v25, 0xffff0000, v22
	v_lshlrev_b32_e32 v22, 16, v23
	v_and_b32_e32 v23, 0xffff0000, v23
	v_pk_fma_f32 v[18:19], v[2:3], v[24:25], v[18:19]
	v_pk_fma_f32 v[20:21], v[4:5], v[22:23], v[20:21]
	global_store_dwordx4 v[72:73], v[18:21], off
	ds_read_b64 v[18:19], v151 offset:54912
	s_waitcnt lgkmcnt(0)
	v_lshlrev_b32_e32 v20, 16, v18
	v_and_b32_e32 v21, 0xffff0000, v18
	v_lshlrev_b32_e32 v18, 16, v19
	v_and_b32_e32 v19, 0xffff0000, v19
	v_pk_fma_f32 v[14:15], v[2:3], v[20:21], v[14:15]
	v_pk_fma_f32 v[16:17], v[4:5], v[18:19], v[16:17]
	global_store_dwordx4 v[66:67], v[14:17], off
	ds_read_b64 v[14:15], v151 offset:59136
	s_waitcnt lgkmcnt(0)
	v_lshlrev_b32_e32 v16, 16, v14
	v_and_b32_e32 v17, 0xffff0000, v14
	v_lshlrev_b32_e32 v14, 16, v15
	v_and_b32_e32 v15, 0xffff0000, v15
	v_pk_fma_f32 v[10:11], v[2:3], v[16:17], v[10:11]
	v_pk_fma_f32 v[12:13], v[4:5], v[14:15], v[12:13]
	global_store_dwordx4 v[64:65], v[10:13], off
	ds_read_b64 v[10:11], v170
	s_waitcnt lgkmcnt(0)
	v_lshlrev_b32_e32 v12, 16, v10
	v_and_b32_e32 v13, 0xffff0000, v10
	v_lshlrev_b32_e32 v10, 16, v11
	v_and_b32_e32 v11, 0xffff0000, v11
	v_pk_fma_f32 v[2:3], v[2:3], v[12:13], v[6:7]
	v_pk_fma_f32 v[4:5], v[4:5], v[10:11], v[8:9]
	global_store_dwordx4 v[62:63], v[2:5], off
	s_nop 1
	v_or_b32_e32 v2, 0x80, v70
	v_ashrrev_i32_e32 v3, 31, v2
	v_lshl_add_u64 v[2:3], v[2:3], 2, s[24:25]
	global_load_dwordx4 v[2:5], v[2:3], off nt
	s_nop 0
	global_load_dwordx4 v[6:9], v[126:127], off offset:512 nt
	global_load_dwordx4 v[10:13], v[124:125], off offset:512 nt
	global_load_dwordx4 v[14:17], v[122:123], off offset:512 nt
	global_load_dwordx4 v[18:21], v[120:121], off offset:512 nt
	global_load_dwordx4 v[22:25], v[118:119], off offset:512 nt
	global_load_dwordx4 v[26:29], v[116:117], off offset:512 nt
	global_load_dwordx4 v[30:33], v[114:115], off offset:512 nt
	global_load_dwordx4 v[34:37], v[110:111], off offset:512 nt
	global_load_dwordx4 v[38:41], v[106:107], off offset:512 nt
	global_load_dwordx4 v[42:45], v[100:101], off offset:512 nt
	global_load_dwordx4 v[46:49], v[94:95], off offset:512 nt
	global_load_dwordx4 v[50:53], v[90:91], off offset:512 nt
	global_load_dwordx4 v[54:57], v[84:85], off offset:512 nt
	global_load_dwordx4 v[58:61], v[78:79], off offset:512 nt
	global_load_dwordx4 v[114:117], v[74:75], off offset:512 nt
	s_nop 0
	global_load_dwordx4 v[68:71], v[68:69], off offset:512 nt
	ds_read_b64 v[74:75], v151 offset:256
	s_waitcnt lgkmcnt(0)
	v_lshlrev_b32_e32 v78, 16, v74
	v_and_b32_e32 v79, 0xffff0000, v74
	v_lshlrev_b32_e32 v74, 16, v75
	v_and_b32_e32 v75, 0xffff0000, v75
	s_waitcnt vmcnt(0)
	v_pk_fma_f32 v[68:69], v[2:3], v[78:79], v[68:69]
	v_pk_fma_f32 v[70:71], v[4:5], v[74:75], v[70:71]
	global_store_dwordx4 v[112:113], v[68:71], off offset:512
	ds_read_b64 v[68:69], v151 offset:4480
	s_waitcnt lgkmcnt(0)
	v_lshlrev_b32_e32 v74, 16, v69
	v_lshlrev_b32_e32 v70, 16, v68
	v_and_b32_e32 v71, 0xffff0000, v68
	v_and_b32_e32 v75, 0xffff0000, v69
	v_pk_fma_f32 v[68:69], v[2:3], v[70:71], v[114:115]
	v_pk_fma_f32 v[70:71], v[4:5], v[74:75], v[116:117]
	global_store_dwordx4 v[108:109], v[68:71], off offset:512
	ds_read_b64 v[68:69], v151 offset:8704
	s_waitcnt lgkmcnt(0)
; DI void phase4(const Params& p, char* lds) {
;     ...
; #pragma unroll
;       for (int ps = 0; ps < 16; ++ps) {
;         const int row = ps * 8 + (tid >> 5), t = t0h + row;
;         float4 c = cs4(Cs, row, c4);
;         float4 o = make_float4(xv[ps].x + g1.x * c.x, xv[ps].y + g1.y * c.y, xv[ps].z + g1.z * c.z, xv[ps].w + g1.w * c.w);
;         *(float4*)(p.out + (size_t)t * D + col) = o;
;       }
	v_lshlrev_b32_e32 v70, 16, v68
	v_and_b32_e32 v71, 0xffff0000, v68
	v_lshlrev_b32_e32 v68, 16, v69
	v_and_b32_e32 v69, 0xffff0000, v69
	v_pk_fma_f32 v[58:59], v[2:3], v[70:71], v[58:59]
	v_pk_fma_f32 v[60:61], v[4:5], v[68:69], v[60:61]
	global_store_dwordx4 v[104:105], v[58:61], off offset:512
	ds_read_b64 v[58:59], v155 offset:256
	s_waitcnt lgkmcnt(0)
	v_lshlrev_b32_e32 v60, 16, v58
	v_and_b32_e32 v61, 0xffff0000, v58
	v_lshlrev_b32_e32 v58, 16, v59
	v_and_b32_e32 v59, 0xffff0000, v59
	v_pk_fma_f32 v[54:55], v[2:3], v[60:61], v[54:55]
	v_pk_fma_f32 v[56:57], v[4:5], v[58:59], v[56:57]
	global_store_dwordx4 v[102:103], v[54:57], off offset:512
	ds_read_b64 v[54:55], v151 offset:17152
	s_waitcnt lgkmcnt(0)
	v_lshlrev_b32_e32 v56, 16, v54
	v_and_b32_e32 v57, 0xffff0000, v54
	v_lshlrev_b32_e32 v54, 16, v55
	v_and_b32_e32 v55, 0xffff0000, v55
	v_pk_fma_f32 v[50:51], v[2:3], v[56:57], v[50:51]
	v_pk_fma_f32 v[52:53], v[4:5], v[54:55], v[52:53]
	global_store_dwordx4 v[98:99], v[50:53], off offset:512
	ds_read_b64 v[50:51], v151 offset:21376
	s_waitcnt lgkmcnt(0)
	v_lshlrev_b32_e32 v52, 16, v50
	v_and_b32_e32 v53, 0xffff0000, v50
	v_lshlrev_b32_e32 v50, 16, v51
	v_and_b32_e32 v51, 0xffff0000, v51
	v_pk_fma_f32 v[46:47], v[2:3], v[52:53], v[46:47]
	v_pk_fma_f32 v[48:49], v[4:5], v[50:51], v[48:49]
	global_store_dwordx4 v[96:97], v[46:49], off offset:512
	ds_read_b64 v[46:47], v151 offset:25600
	s_waitcnt lgkmcnt(0)
	v_lshlrev_b32_e32 v48, 16, v46
	v_and_b32_e32 v49, 0xffff0000, v46
	v_lshlrev_b32_e32 v46, 16, v47
	v_and_b32_e32 v47, 0xffff0000, v47
	v_pk_fma_f32 v[42:43], v[2:3], v[48:49], v[42:43]
	v_pk_fma_f32 v[44:45], v[4:5], v[46:47], v[44:45]
	global_store_dwordx4 v[92:93], v[42:45], off offset:512
	ds_read_b64 v[42:43], v160 offset:256
	s_waitcnt lgkmcnt(0)
	v_lshlrev_b32_e32 v44, 16, v42
	v_and_b32_e32 v45, 0xffff0000, v42
	v_lshlrev_b32_e32 v42, 16, v43
	v_and_b32_e32 v43, 0xffff0000, v43
	v_pk_fma_f32 v[38:39], v[2:3], v[44:45], v[38:39]
	v_pk_fma_f32 v[40:41], v[4:5], v[42:43], v[40:41]
	global_store_dwordx4 v[88:89], v[38:41], off offset:512
	ds_read_b64 v[38:39], v151 offset:34048
	s_waitcnt lgkmcnt(0)
	v_lshlrev_b32_e32 v40, 16, v38
	v_and_b32_e32 v41, 0xffff0000, v38
	v_lshlrev_b32_e32 v38, 16, v39
	v_and_b32_e32 v39, 0xffff0000, v39
	v_pk_fma_f32 v[34:35], v[2:3], v[40:41], v[34:35]
	v_pk_fma_f32 v[36:37], v[4:5], v[38:39], v[36:37]
	global_store_dwordx4 v[86:87], v[34:37], off offset:512
	ds_read_b64 v[34:35], v151 offset:38272
	s_waitcnt lgkmcnt(0)
	v_lshlrev_b32_e32 v36, 16, v34
	v_and_b32_e32 v37, 0xffff0000, v34
	v_lshlrev_b32_e32 v34, 16, v35
	v_and_b32_e32 v35, 0xffff0000, v35
	v_pk_fma_f32 v[30:31], v[2:3], v[36:37], v[30:31]
	v_pk_fma_f32 v[32:33], v[4:5], v[34:35], v[32:33]
	global_store_dwordx4 v[82:83], v[30:33], off offset:512
	ds_read_b64 v[30:31], v151 offset:42496
	s_waitcnt lgkmcnt(0)
	v_lshlrev_b32_e32 v32, 16, v30
	v_and_b32_e32 v33, 0xffff0000, v30
	v_lshlrev_b32_e32 v30, 16, v31
	v_and_b32_e32 v31, 0xffff0000, v31
	v_pk_fma_f32 v[26:27], v[2:3], v[32:33], v[26:27]
	v_pk_fma_f32 v[28:29], v[4:5], v[30:31], v[28:29]
	global_store_dwordx4 v[80:81], v[26:29], off offset:512
	ds_read_b64 v[26:27], v165 offset:256
	s_waitcnt lgkmcnt(0)
	v_lshlrev_b32_e32 v28, 16, v26
	v_and_b32_e32 v29, 0xffff0000, v26
	v_lshlrev_b32_e32 v26, 16, v27
	v_and_b32_e32 v27, 0xffff0000, v27
	v_pk_fma_f32 v[22:23], v[2:3], v[28:29], v[22:23]
	v_pk_fma_f32 v[24:25], v[4:5], v[26:27], v[24:25]
	global_store_dwordx4 v[76:77], v[22:25], off offset:512
	ds_read_b64 v[22:23], v151 offset:50944
	s_waitcnt lgkmcnt(0)
	v_lshlrev_b32_e32 v24, 16, v22
	v_and_b32_e32 v25, 0xffff0000, v22
	v_lshlrev_b32_e32 v22, 16, v23
	v_and_b32_e32 v23, 0xffff0000, v23
	v_pk_fma_f32 v[18:19], v[2:3], v[24:25], v[18:19]
	v_pk_fma_f32 v[20:21], v[4:5], v[22:23], v[20:21]
	global_store_dwordx4 v[72:73], v[18:21], off offset:512
	ds_read_b64 v[18:19], v151 offset:55168
	s_waitcnt lgkmcnt(0)
	v_lshlrev_b32_e32 v20, 16, v18
	v_and_b32_e32 v21, 0xffff0000, v18
	v_lshlrev_b32_e32 v18, 16, v19
	v_and_b32_e32 v19, 0xffff0000, v19
	v_pk_fma_f32 v[14:15], v[2:3], v[20:21], v[14:15]
	v_pk_fma_f32 v[16:17], v[4:5], v[18:19], v[16:17]
	global_store_dwordx4 v[66:67], v[14:17], off offset:512
	ds_read_b64 v[14:15], v151 offset:59392
	s_waitcnt lgkmcnt(0)
	v_lshlrev_b32_e32 v16, 16, v14
	v_and_b32_e32 v17, 0xffff0000, v14
	v_lshlrev_b32_e32 v14, 16, v15
	v_and_b32_e32 v15, 0xffff0000, v15
	v_pk_fma_f32 v[10:11], v[2:3], v[16:17], v[10:11]
	v_pk_fma_f32 v[12:13], v[4:5], v[14:15], v[12:13]
	global_store_dwordx4 v[64:65], v[10:13], off offset:512
	ds_read_b64 v[10:11], v170 offset:256
	s_waitcnt lgkmcnt(0)
	v_lshlrev_b32_e32 v12, 16, v10
	v_and_b32_e32 v13, 0xffff0000, v10
	v_lshlrev_b32_e32 v10, 16, v11
	v_and_b32_e32 v11, 0xffff0000, v11
	v_pk_fma_f32 v[2:3], v[2:3], v[12:13], v[6:7]
	v_pk_fma_f32 v[4:5], v[4:5], v[10:11], v[8:9]
	global_store_dwordx4 v[62:63], v[2:5], off offset:512
	s_barrier
	s_cbranch_scc1 .LBB0_229

; DI void phase5(const Params& p, char* lds0) {
;     ...
;       if (i + 1 < 8) {
;         const float* x1 = p.out + (size_t)(t + 2) * D;
; #pragma unroll
;         for (int j = 0; j < 8; ++j) nx[j] = *(const float4*)(x1 + j * 128 + l32 * 4);
;       }
.LBB0_256:
	s_cmp_eq_u32 s44, 14
	v_add_u32_e32 v158, s44, v181
	s_cbranch_scc1 .LBB0_258
	v_add_u32_e32 v34, 2, v158
	v_ashrrev_i32_e32 v35, 31, v34
	v_lshlrev_b64 v[34:35], 12, v[34:35]
	v_lshl_add_u64 v[62:63], v[108:109], 0, v[34:35]
	global_load_dwordx4 v[34:37], v[62:63], off nt
	global_load_dwordx4 v[38:41], v[62:63], off offset:512 nt
	global_load_dwordx4 v[42:45], v[62:63], off offset:1024 nt
	global_load_dwordx4 v[46:49], v[62:63], off offset:1536 nt
	global_load_dwordx4 v[50:53], v[62:63], off offset:2048 nt
	global_load_dwordx4 v[54:57], v[62:63], off offset:2560 nt
	global_load_dwordx4 v[58:61], v[62:63], off offset:3072 nt
	s_nop 0
	global_load_dwordx4 v[62:65], v[62:63], off offset:3584 nt
	s_branch .LBB0_259

; #define MFMA(a, b, c) __builtin_amdgcn_mfma_f32_32x32x16_bf16((a), (b), (c), 0, 0, 0)
; DI unsigned pk2(float a, float b) { fl2_t f = {a, b}; bf2_t r = __builtin_convertvector(f, bf2_t); return __builtin_bit_cast(unsigned, r); }
; #define WAIT_V(n) asm volatile("s_waitcnt vmcnt(%0)" ::"n"(n) : "memory")
; #define RAW_BARRIER() do { asm volatile("s_waitcnt lgkmcnt(0)" ::: "memory"); __builtin_amdgcn_s_barrier(); } while (0)
; template <typename FA, typename FB, typename FE>
; DI void gemm_tile(char* lds, int K, int astride, int bstride, FA arow, FB brow, FE epi) {
;     ...
;   for (int kt = 0; kt < nk; ++kt) {
;     if (kt + 2 < nk) WAIT_V(8); else if (kt + 1 < nk) WAIT_V(4); else WAIT_V(0);
;     RAW_BARRIER();
;     if (kt + 3 < nk) stage((kt + 3) & 3, kt + 3);
;     const char* sa = lds + (kt & 3) * 32768 + wm * 4096;
;     const char* sb = lds + (kt & 3) * 32768 + 16384 + wn * 8192;
; #pragma unroll
;     for (int ks = 0; ks < 2; ++ks) {
;       bf16x8 a0 = *(const bf16x8*)(sa + foff[ks]), a1 = *(const bf16x8*)(sa + 2048 + foff[ks]);
; #pragma unroll
;       for (int nt = 0; nt < 4; ++nt) {
;         bf16x8 bb = *(const bf16x8*)(sb + nt * 2048 + foff[ks]);
;         acc[0][nt] = MFMA(a0, bb, acc[0][nt]);
;         acc[1][nt] = MFMA(a1, bb, acc[1][nt]);
;       }
;     }
;   }
;   RAW_BARRIER();
;   bfr* Cs = (bfr*)lds;
; #pragma unroll
;   for (int mt = 0; mt < 2; ++mt)
; #pragma unroll
;     for (int nt = 0; nt < 4; ++nt)
; #pragma unroll
;       for (int i = 0; i < 16; i += 2) {
;         const int row = wm * 64 + mt * 32 + (i & 3) + 8 * (i >> 2) + 4 * h8;
;         const unsigned pr = pk2(acc[mt][nt][i], acc[mt][nt][i + 1]);
;         Cs[row * CSS + wn * 128 + nt * 32 + r] = (bfr)(pr & 0xffffu);
;         Cs[(row + 1) * CSS + wn * 128 + nt * 32 + r] = (bfr)(pr >> 16);
;       }
.Lgf_P8_wd:
	s_mov_b32 m0, s6
	s_barrier
	s_add_i32 s7, s5, 0xfffe8000
	s_and_b32 s7, s7, 0x18000
	s_add_i32 s8, s7, s21
	s_or_b32 s7, s7, s22
	v_add_u32_e32 v254, s8, v190
	v_add_u32_e32 v255, s7, v190
	s_waitcnt lgkmcnt(4)
	v_mfma_f32_32x32x16_bf16 v[112:127], v[154:157], v[162:165], v[112:127]
	s_mov_b64 exec, s[10:11]
	global_load_lds_dwordx4 v[136:137], off
	s_mov_b64 exec, -1
	s_add_i32 m0, s6, 0x4000
	ds_read_b128 v[178:181], v254
	s_waitcnt lgkmcnt(4)
	v_mfma_f32_32x32x16_bf16 v[48:63], v[158:161], v[162:165], v[48:63]
	s_mov_b64 exec, s[10:11]
	global_load_lds_dwordx4 v[138:139], off
	s_mov_b64 exec, -1
	s_add_i32 m0, s6, 0x400
	ds_read_b128 v[232:235], v255 offset:16384
	s_waitcnt lgkmcnt(4)
	v_mfma_f32_32x32x16_bf16 v[96:111], v[154:157], v[166:169], v[96:111]
	s_mov_b64 exec, s[10:11]
	global_load_lds_dwordx4 v[140:141], off
	s_mov_b64 exec, -1
	s_add_i32 m0, s6, 0x4400
	ds_read_b128 v[182:185], v254 offset:2048
	v_mfma_f32_32x32x16_bf16 v[32:47], v[158:161], v[166:169], v[32:47]
	ds_read_b128 v[236:239], v255 offset:18432
	s_mov_b64 exec, s[10:11]
	global_load_lds_dwordx4 v[142:143], off
	s_mov_b64 exec, -1
	s_waitcnt lgkmcnt(5)
	v_mfma_f32_32x32x16_bf16 v[80:95], v[154:157], v[170:173], v[80:95]
	ds_read_b128 v[240:243], v255 offset:20480
	v_lshl_add_u64 v[138:139], v[138:139], 0, s[14:15]
	v_lshl_add_u64 v[142:143], v[142:143], 0, s[14:15]
	v_mfma_f32_32x32x16_bf16 v[16:31], v[158:161], v[170:173], v[16:31]
	ds_read_b128 v[248:251], v255 offset:22528
	v_lshl_add_u64 v[136:137], v[136:137], 0, s[12:13]
	v_lshl_add_u64 v[140:141], v[140:141], 0, s[12:13]
	s_waitcnt lgkmcnt(6)
	v_mfma_f32_32x32x16_bf16 v[64:79], v[154:157], v[174:177], v[64:79]
	s_add_i32 s7, s5, 0xffff0000
	s_and_b32 s7, s7, 0x18000
	s_add_i32 s8, s7, s21
	s_or_b32 s7, s7, s22
	v_mfma_f32_32x32x16_bf16 v[0:15], v[158:161], v[174:177], v[0:15]
	v_add_u32_e32 v252, s8, v189
	v_add_u32_e32 v253, s7, v189
	s_waitcnt lgkmcnt(4)
	v_mfma_f32_32x32x16_bf16 v[112:127], v[178:181], v[232:235], v[112:127]
	ds_read_b128 v[154:157], v252
	s_waitcnt lgkmcnt(4)
	v_mfma_f32_32x32x16_bf16 v[48:63], v[182:185], v[232:235], v[48:63]
	ds_read_b128 v[162:165], v253 offset:16384
	s_waitcnt lgkmcnt(4)
	v_mfma_f32_32x32x16_bf16 v[96:111], v[178:181], v[236:239], v[96:111]
	ds_read_b128 v[158:161], v252 offset:2048
	v_mfma_f32_32x32x16_bf16 v[32:47], v[182:185], v[236:239], v[32:47]
	ds_read_b128 v[166:169], v253 offset:18432
	s_waitcnt lgkmcnt(5)
	v_mfma_f32_32x32x16_bf16 v[80:95], v[178:181], v[240:243], v[80:95]
	ds_read_b128 v[170:173], v253 offset:20480
	v_mfma_f32_32x32x16_bf16 v[16:31], v[182:185], v[240:243], v[16:31]
	ds_read_b128 v[174:177], v253 offset:22528
	s_waitcnt lgkmcnt(6)
	v_mfma_f32_32x32x16_bf16 v[64:79], v[178:181], v[248:251], v[64:79]
	s_add_i32 s5, s5, 0x8000
	v_mfma_f32_32x32x16_bf16 v[0:15], v[182:185], v[248:251], v[0:15]
	s_cmp_eq_u32 s5, 0x98000
	s_cbranch_scc0 .Lgf_P8_loop
	s_waitcnt lgkmcnt(0)
	s_barrier
	s_nop 15
	v_lshl_or_b32 v128, s1, 6, v191
	s_movk_i32 s1, 0x210
	s_nop 10
	v_cvt_pk_bf16_f32 v96, v96, v97
	v_cvt_pk_bf16_f32 v136, v112, v113
	v_lshl_or_b32 v112, s4, 8, v216
	v_mad_u64_u32 v[112:113], s[4:5], v128, s1, v[112:113]
	v_cvt_pk_bf16_f32 v113, v114, v115
	ds_write_b16 v112, v136
	ds_write_b16_d16_hi v112, v136 offset:528
	ds_write_b16 v112, v113 offset:1056
	ds_write_b16_d16_hi v112, v113 offset:1584
	v_cvt_pk_bf16_f32 v113, v116, v117
	ds_write_b16 v112, v113 offset:4224
	ds_write_b16_d16_hi v112, v113 offset:4752
	v_cvt_pk_bf16_f32 v113, v118, v119
	ds_write_b16 v112, v113 offset:5280
	ds_write_b16_d16_hi v112, v113 offset:5808
	v_cvt_pk_bf16_f32 v113, v120, v121
	ds_write_b16 v112, v113 offset:8448
	ds_write_b16_d16_hi v112, v113 offset:8976
	v_cvt_pk_bf16_f32 v113, v122, v123
	ds_write_b16 v112, v113 offset:9504
	ds_write_b16_d16_hi v112, v113 offset:10032
	v_cvt_pk_bf16_f32 v113, v124, v125
	ds_write_b16 v112, v113 offset:12672
	ds_write_b16_d16_hi v112, v113 offset:13200
	v_cvt_pk_bf16_f32 v113, v126, v127
	ds_write_b16 v112, v113 offset:13728
	ds_write_b16_d16_hi v112, v113 offset:14256
	ds_write_b16 v112, v96 offset:64
	ds_write_b16_d16_hi v112, v96 offset:592
	v_cvt_pk_bf16_f32 v96, v98, v99
	ds_write_b16 v112, v96 offset:1120
	ds_write_b16_d16_hi v112, v96 offset:1648
	v_cvt_pk_bf16_f32 v96, v100, v101
	ds_write_b16 v112, v96 offset:4288
	ds_write_b16_d16_hi v112, v96 offset:4816
	v_cvt_pk_bf16_f32 v96, v102, v103
	ds_write_b16 v112, v96 offset:5344
	ds_write_b16_d16_hi v112, v96 offset:5872
	v_cvt_pk_bf16_f32 v96, v104, v105
	ds_write_b16 v112, v96 offset:8512
	ds_write_b16_d16_hi v112, v96 offset:9040
	v_cvt_pk_bf16_f32 v96, v106, v107
	ds_write_b16 v112, v96 offset:9568
	ds_write_b16_d16_hi v112, v96 offset:10096
	v_cvt_pk_bf16_f32 v96, v108, v109
	ds_write_b16 v112, v96 offset:12736
	ds_write_b16_d16_hi v112, v96 offset:13264
	v_cvt_pk_bf16_f32 v96, v110, v111
	v_cvt_pk_bf16_f32 v80, v80, v81
	ds_write_b16 v112, v96 offset:13792
	ds_write_b16_d16_hi v112, v96 offset:14320
	ds_write_b16 v112, v80 offset:128
	ds_write_b16_d16_hi v112, v80 offset:656
	v_cvt_pk_bf16_f32 v80, v82, v83
	ds_write_b16 v112, v80 offset:1184
	ds_write_b16_d16_hi v112, v80 offset:1712
	v_cvt_pk_bf16_f32 v80, v84, v85
	ds_write_b16 v112, v80 offset:4352
	ds_write_b16_d16_hi v112, v80 offset:4880
	v_cvt_pk_bf16_f32 v80, v86, v87
	ds_write_b16 v112, v80 offset:5408
	ds_write_b16_d16_hi v112, v80 offset:5936
	v_cvt_pk_bf16_f32 v80, v88, v89
	ds_write_b16 v112, v80 offset:8576
	ds_write_b16_d16_hi v112, v80 offset:9104
	v_cvt_pk_bf16_f32 v80, v90, v91
	ds_write_b16 v112, v80 offset:9632
	ds_write_b16_d16_hi v112, v80 offset:10160
	v_cvt_pk_bf16_f32 v80, v92, v93
; DI unsigned pk2(float a, float b) { fl2_t f = {a, b}; bf2_t r = __builtin_convertvector(f, bf2_t); return __builtin_bit_cast(unsigned, r); }
; template <typename FA, typename FB, typename FE>
; DI void gemm_tile(char* lds, int K, int astride, int bstride, FA arow, FB brow, FE epi) {
;     ...
; #pragma unroll
;   for (int mt = 0; mt < 2; ++mt)
; #pragma unroll
;     for (int nt = 0; nt < 4; ++nt)
; #pragma unroll
;       for (int i = 0; i < 16; i += 2) {
;         const int row = wm * 64 + mt * 32 + (i & 3) + 8 * (i >> 2) + 4 * h8;
;         const unsigned pr = pk2(acc[mt][nt][i], acc[mt][nt][i + 1]);
;         Cs[row * CSS + wn * 128 + nt * 32 + r] = (bfr)(pr & 0xffffu);
;         Cs[(row + 1) * CSS + wn * 128 + nt * 32 + r] = (bfr)(pr >> 16);
;       }
;   __syncthreads();
	ds_write_b16 v112, v80 offset:12800
	ds_write_b16_d16_hi v112, v80 offset:13328
	v_cvt_pk_bf16_f32 v80, v94, v95
	v_cvt_pk_bf16_f32 v64, v64, v65
	ds_write_b16 v112, v80 offset:13856
	ds_write_b16_d16_hi v112, v80 offset:14384
	ds_write_b16 v112, v64 offset:192
	ds_write_b16_d16_hi v112, v64 offset:720
	v_cvt_pk_bf16_f32 v64, v66, v67
	ds_write_b16 v112, v64 offset:1248
	ds_write_b16_d16_hi v112, v64 offset:1776
	v_cvt_pk_bf16_f32 v64, v68, v69
	ds_write_b16 v112, v64 offset:4416
	ds_write_b16_d16_hi v112, v64 offset:4944
	v_cvt_pk_bf16_f32 v64, v70, v71
	ds_write_b16 v112, v64 offset:5472
	ds_write_b16_d16_hi v112, v64 offset:6000
	v_cvt_pk_bf16_f32 v64, v72, v73
	ds_write_b16 v112, v64 offset:8640
	ds_write_b16_d16_hi v112, v64 offset:9168
	v_cvt_pk_bf16_f32 v64, v74, v75
	ds_write_b16 v112, v64 offset:9696
	ds_write_b16_d16_hi v112, v64 offset:10224
	v_cvt_pk_bf16_f32 v64, v76, v77
	ds_write_b16 v112, v64 offset:12864
	ds_write_b16_d16_hi v112, v64 offset:13392
	v_cvt_pk_bf16_f32 v64, v78, v79
	v_cvt_pk_bf16_f32 v48, v48, v49
	ds_write_b16 v112, v64 offset:13920
	ds_write_b16_d16_hi v112, v64 offset:14448
	ds_write_b16 v112, v48 offset:16896
	ds_write_b16_d16_hi v112, v48 offset:17424
	v_cvt_pk_bf16_f32 v48, v50, v51
	ds_write_b16 v112, v48 offset:17952
	ds_write_b16_d16_hi v112, v48 offset:18480
	v_cvt_pk_bf16_f32 v48, v52, v53
	ds_write_b16 v112, v48 offset:21120
	ds_write_b16_d16_hi v112, v48 offset:21648
	v_cvt_pk_bf16_f32 v48, v54, v55
	ds_write_b16 v112, v48 offset:22176
	ds_write_b16_d16_hi v112, v48 offset:22704
	v_cvt_pk_bf16_f32 v48, v56, v57
	ds_write_b16 v112, v48 offset:25344
	ds_write_b16_d16_hi v112, v48 offset:25872
	v_cvt_pk_bf16_f32 v48, v58, v59
	ds_write_b16 v112, v48 offset:26400
	ds_write_b16_d16_hi v112, v48 offset:26928
	v_cvt_pk_bf16_f32 v48, v60, v61
	ds_write_b16 v112, v48 offset:29568
	ds_write_b16_d16_hi v112, v48 offset:30096
	v_cvt_pk_bf16_f32 v48, v62, v63
	v_cvt_pk_bf16_f32 v32, v32, v33
	ds_write_b16 v112, v48 offset:30624
	ds_write_b16_d16_hi v112, v48 offset:31152
	ds_write_b16 v112, v32 offset:16960
	ds_write_b16_d16_hi v112, v32 offset:17488
	v_cvt_pk_bf16_f32 v32, v34, v35
	ds_write_b16 v112, v32 offset:18016
	ds_write_b16_d16_hi v112, v32 offset:18544
	v_cvt_pk_bf16_f32 v32, v36, v37
	ds_write_b16 v112, v32 offset:21184
	ds_write_b16_d16_hi v112, v32 offset:21712
	v_cvt_pk_bf16_f32 v32, v38, v39
	ds_write_b16 v112, v32 offset:22240
	ds_write_b16_d16_hi v112, v32 offset:22768
	v_cvt_pk_bf16_f32 v32, v40, v41
	ds_write_b16 v112, v32 offset:25408
	ds_write_b16_d16_hi v112, v32 offset:25936
	v_cvt_pk_bf16_f32 v32, v42, v43
	ds_write_b16 v112, v32 offset:26464
	ds_write_b16_d16_hi v112, v32 offset:26992
	v_cvt_pk_bf16_f32 v32, v44, v45
	ds_write_b16 v112, v32 offset:29632
	ds_write_b16_d16_hi v112, v32 offset:30160
	v_cvt_pk_bf16_f32 v32, v46, v47
	v_cvt_pk_bf16_f32 v16, v16, v17
	ds_write_b16 v112, v32 offset:30688
	ds_write_b16_d16_hi v112, v32 offset:31216
	ds_write_b16 v112, v16 offset:17024
	ds_write_b16_d16_hi v112, v16 offset:17552
	v_cvt_pk_bf16_f32 v16, v18, v19
	ds_write_b16 v112, v16 offset:18080
	ds_write_b16_d16_hi v112, v16 offset:18608
	v_cvt_pk_bf16_f32 v16, v20, v21
	ds_write_b16 v112, v16 offset:21248
	ds_write_b16_d16_hi v112, v16 offset:21776
	v_cvt_pk_bf16_f32 v16, v22, v23
	ds_write_b16 v112, v16 offset:22304
	ds_write_b16_d16_hi v112, v16 offset:22832
	v_cvt_pk_bf16_f32 v16, v24, v25
	ds_write_b16 v112, v16 offset:25472
	ds_write_b16_d16_hi v112, v16 offset:26000
	v_cvt_pk_bf16_f32 v16, v26, v27
	ds_write_b16 v112, v16 offset:26528
	ds_write_b16_d16_hi v112, v16 offset:27056
	v_cvt_pk_bf16_f32 v16, v28, v29
	ds_write_b16 v112, v16 offset:29696
	ds_write_b16_d16_hi v112, v16 offset:30224
	v_cvt_pk_bf16_f32 v16, v30, v31
	v_cvt_pk_bf16_f32 v0, v0, v1
	ds_write_b16 v112, v16 offset:30752
	ds_write_b16_d16_hi v112, v16 offset:31280
	ds_write_b16 v112, v0 offset:17088
	ds_write_b16_d16_hi v112, v0 offset:17616
	v_cvt_pk_bf16_f32 v0, v2, v3
	ds_write_b16 v112, v0 offset:18144
	ds_write_b16_d16_hi v112, v0 offset:18672
	v_cvt_pk_bf16_f32 v0, v4, v5
	ds_write_b16 v112, v0 offset:21312
	ds_write_b16_d16_hi v112, v0 offset:21840
	v_cvt_pk_bf16_f32 v0, v6, v7
	ds_write_b16 v112, v0 offset:22368
	ds_write_b16_d16_hi v112, v0 offset:22896
	v_cvt_pk_bf16_f32 v0, v8, v9
	ds_write_b16 v112, v0 offset:25536
	ds_write_b16_d16_hi v112, v0 offset:26064
	v_cvt_pk_bf16_f32 v0, v10, v11
	ds_write_b16 v112, v0 offset:26592
	ds_write_b16_d16_hi v112, v0 offset:27120
	v_cvt_pk_bf16_f32 v0, v12, v13
	ds_write_b16 v112, v0 offset:29760
	ds_write_b16_d16_hi v112, v0 offset:30288
	v_cvt_pk_bf16_f32 v0, v14, v15
	ds_write_b16 v112, v0 offset:30816
	ds_write_b16_d16_hi v112, v0 offset:31344
	s_waitcnt vmcnt(0) lgkmcnt(0)
	s_barrier
; DI void phase_moe(const Params& p, char* lds, int mode) {
;     ...
;           float4 ov[16]; u32x2 yv[16]; float gt[16]; int tk[16];
; #pragma unroll
;           for (int ps = 0; ps < 16; ++ps) {
;             const int grow = half * 128 + ps * 8 + (tid >> 5);
;             tk[ps] = rowtok[grow];
;             gt[ps] = gate[(size_t)k * T + tk[ps]];
;             ov[ps] = *(const float4*)(p.out + (size_t)tk[ps] * D + col);
;             yv[ps] = *(const u32x2*)(Y0 + (size_t)tk[ps] * D + col);
;           }
	ds_read2_b32 v[168:169], v194 offset1:8
	v_or_b32_e32 v64, s0, v192
	v_ashrrev_i32_e32 v65, 31, v64
	v_lshl_add_u64 v[72:73], v[64:65], 1, s[42:43]
	ds_read2_b32 v[154:155], v194 offset0:16 offset1:24
	s_waitcnt lgkmcnt(1)
	v_ashrrev_i32_e32 v1, 31, v168
	v_mov_b32_e32 v0, v168
	v_lshl_add_u64 v[2:3], v[0:1], 2, s[44:45]
	v_lshlrev_b64 v[184:185], 12, v[0:1]
	v_lshlrev_b64 v[0:1], 11, v[0:1]
	v_lshl_add_u64 v[66:67], v[64:65], 2, s[46:47]
	v_lshl_add_u64 v[0:1], v[72:73], 0, v[0:1]
	global_load_dword v180, v[2:3], off
	v_lshl_add_u64 v[2:3], v[66:67], 0, v[184:185]
	global_load_dwordx2 v[182:183], v[0:1], off nt
	v_ashrrev_i32_e32 v1, 31, v169
	v_mov_b32_e32 v0, v169
	global_load_dwordx4 v[60:63], v[2:3], off nt
	v_lshl_add_u64 v[2:3], v[0:1], 2, s[44:45]
	v_lshlrev_b64 v[178:179], 12, v[0:1]
	v_lshlrev_b64 v[0:1], 11, v[0:1]
	v_lshl_add_u64 v[0:1], v[72:73], 0, v[0:1]
	global_load_dword v172, v[2:3], off
	v_lshl_add_u64 v[2:3], v[66:67], 0, v[178:179]
	global_load_dwordx2 v[174:175], v[0:1], off nt
	s_waitcnt lgkmcnt(0)
	v_ashrrev_i32_e32 v1, 31, v154
	v_mov_b32_e32 v0, v154
	global_load_dwordx4 v[56:59], v[2:3], off nt
	v_lshl_add_u64 v[2:3], v[0:1], 2, s[44:45]
	v_lshlrev_b64 v[176:177], 12, v[0:1]
	v_lshlrev_b64 v[0:1], 11, v[0:1]
	ds_read2_b32 v[140:141], v194 offset0:32 offset1:40
	v_lshl_add_u64 v[0:1], v[72:73], 0, v[0:1]
	global_load_dword v166, v[2:3], off
	v_lshl_add_u64 v[2:3], v[66:67], 0, v[176:177]
	global_load_dwordx2 v[170:171], v[0:1], off nt
	v_ashrrev_i32_e32 v1, 31, v155
	v_mov_b32_e32 v0, v155
	global_load_dwordx4 v[52:55], v[2:3], off nt
	v_lshl_add_u64 v[2:3], v[0:1], 2, s[44:45]
	v_lshlrev_b64 v[164:165], 12, v[0:1]
	v_lshlrev_b64 v[0:1], 11, v[0:1]
	v_lshl_add_u64 v[0:1], v[72:73], 0, v[0:1]
	global_load_dword v158, v[2:3], off
	v_lshl_add_u64 v[2:3], v[66:67], 0, v[164:165]
	global_load_dwordx2 v[160:161], v[0:1], off nt
	s_waitcnt lgkmcnt(0)
	v_ashrrev_i32_e32 v1, 31, v140
	v_mov_b32_e32 v0, v140
	global_load_dwordx4 v[48:51], v[2:3], off nt
	v_lshl_add_u64 v[2:3], v[0:1], 2, s[44:45]
	v_lshlrev_b64 v[162:163], 12, v[0:1]
	v_lshlrev_b64 v[0:1], 11, v[0:1]
	ds_read2_b32 v[120:121], v194 offset0:48 offset1:56
	v_lshl_add_u64 v[0:1], v[72:73], 0, v[0:1]
	global_load_dword v152, v[2:3], off
	v_lshl_add_u64 v[2:3], v[66:67], 0, v[162:163]
	global_load_dwordx2 v[156:157], v[0:1], off nt
	v_ashrrev_i32_e32 v1, 31, v141
	v_mov_b32_e32 v0, v141
	global_load_dwordx4 v[44:47], v[2:3], off nt
	v_lshl_add_u64 v[2:3], v[0:1], 2, s[44:45]
	v_lshlrev_b64 v[150:151], 12, v[0:1]
	v_lshlrev_b64 v[0:1], 11, v[0:1]
	v_lshl_add_u64 v[0:1], v[72:73], 0, v[0:1]
	global_load_dword v144, v[2:3], off
	v_lshl_add_u64 v[2:3], v[66:67], 0, v[150:151]
	global_load_dwordx2 v[146:147], v[0:1], off nt
	s_waitcnt lgkmcnt(0)
	v_ashrrev_i32_e32 v1, 31, v120
	v_mov_b32_e32 v0, v120
	global_load_dwordx4 v[40:43], v[2:3], off nt
	v_lshl_add_u64 v[2:3], v[0:1], 2, s[44:45]
	v_lshlrev_b64 v[148:149], 12, v[0:1]
	v_lshlrev_b64 v[0:1], 11, v[0:1]
	ds_read2_b32 v[106:107], v194 offset0:64 offset1:72
	v_lshl_add_u64 v[0:1], v[72:73], 0, v[0:1]
	global_load_dword v128, v[2:3], off
	v_lshl_add_u64 v[2:3], v[66:67], 0, v[148:149]
	global_load_dwordx2 v[142:143], v[0:1], off nt
	v_ashrrev_i32_e32 v1, 31, v121
	v_mov_b32_e32 v0, v121
	global_load_dwordx4 v[36:39], v[2:3], off nt
	v_lshl_add_u64 v[2:3], v[0:1], 2, s[44:45]
	v_lshlrev_b64 v[138:139], 12, v[0:1]
	v_lshlrev_b64 v[0:1], 11, v[0:1]
	v_lshl_add_u64 v[0:1], v[72:73], 0, v[0:1]
	global_load_dword v124, v[2:3], off
	v_lshl_add_u64 v[2:3], v[66:67], 0, v[138:139]
	global_load_dwordx2 v[126:127], v[0:1], off nt
	s_waitcnt lgkmcnt(0)
	v_ashrrev_i32_e32 v1, 31, v106
	v_mov_b32_e32 v0, v106
	global_load_dwordx4 v[32:35], v[2:3], off nt
	v_lshl_add_u64 v[2:3], v[0:1], 2, s[44:45]
	v_lshlrev_b64 v[136:137], 12, v[0:1]
	v_lshlrev_b64 v[0:1], 11, v[0:1]
	ds_read2_b32 v[92:93], v194 offset0:80 offset1:88
	v_lshl_add_u64 v[0:1], v[72:73], 0, v[0:1]
	global_load_dword v118, v[2:3], off
	v_lshl_add_u64 v[2:3], v[66:67], 0, v[136:137]
	global_load_dwordx2 v[122:123], v[0:1], off nt
	v_ashrrev_i32_e32 v1, 31, v107
	v_mov_b32_e32 v0, v107
	global_load_dwordx4 v[28:31], v[2:3], off nt
	v_lshl_add_u64 v[2:3], v[0:1], 2, s[44:45]
	v_lshlrev_b64 v[116:117], 12, v[0:1]
	v_lshlrev_b64 v[0:1], 11, v[0:1]
	v_lshl_add_u64 v[0:1], v[72:73], 0, v[0:1]
	global_load_dword v110, v[2:3], off
	v_lshl_add_u64 v[2:3], v[66:67], 0, v[116:117]
	global_load_dwordx2 v[112:113], v[0:1], off nt
	s_waitcnt lgkmcnt(0)
; DI void phase_moe(const Params& p, char* lds, int mode) {
;     ...
;           float4 ov[16]; u32x2 yv[16]; float gt[16]; int tk[16];
; #pragma unroll
;           for (int ps = 0; ps < 16; ++ps) {
;             const int grow = half * 128 + ps * 8 + (tid >> 5);
;             tk[ps] = rowtok[grow];
;             gt[ps] = gate[(size_t)k * T + tk[ps]];
;             ov[ps] = *(const float4*)(p.out + (size_t)tk[ps] * D + col);
;             yv[ps] = *(const u32x2*)(Y0 + (size_t)tk[ps] * D + col);
;           }
;           asm volatile("" ::: "memory");
; #pragma unroll
;           for (int ps = 0; ps < 16; ++ps) {
;             const int row = ps * 8 + (tid >> 5);
;             if (r0 + half * 128 + row < n) {
;               int br, s_, S_; tok_info(tk[ps], br, s_, S_);
;               const float4 g2 = *(const float4*)(g2t + br * 256 + ch * 128 + c4);
;               float4 c = cs4(Cs, row, c4);
;               float4 o = ov[ps];
;               const float g = gt[ps];
;               o.x += g2.x * (__uint_as_float(yv[ps][0] << 16) + g * c.x);
;               o.y += g2.y * (__uint_as_float(yv[ps][0] & 0xffff0000u) + g * c.y);
;               o.z += g2.z * (__uint_as_float(yv[ps][1] << 16) + g * c.z);
;               o.w += g2.w * (__uint_as_float(yv[ps][1] & 0xffff0000u) + g * c.w);
;               *(float4*)(p.out + (size_t)tk[ps] * D + col) = o;
	v_ashrrev_i32_e32 v1, 31, v92
	v_mov_b32_e32 v0, v92
	global_load_dwordx4 v[24:27], v[2:3], off nt
	v_lshl_add_u64 v[2:3], v[0:1], 2, s[44:45]
	v_lshlrev_b64 v[114:115], 12, v[0:1]
	v_lshlrev_b64 v[0:1], 11, v[0:1]
	ds_read2_b32 v[78:79], v194 offset0:96 offset1:104
	v_lshl_add_u64 v[0:1], v[72:73], 0, v[0:1]
	global_load_dword v104, v[2:3], off
	v_lshl_add_u64 v[2:3], v[66:67], 0, v[114:115]
	global_load_dwordx2 v[108:109], v[0:1], off nt
	v_ashrrev_i32_e32 v1, 31, v93
	v_mov_b32_e32 v0, v93
	global_load_dwordx4 v[20:23], v[2:3], off nt
	v_lshl_add_u64 v[2:3], v[0:1], 2, s[44:45]
	v_lshlrev_b64 v[102:103], 12, v[0:1]
	v_lshlrev_b64 v[0:1], 11, v[0:1]
	v_lshl_add_u64 v[0:1], v[72:73], 0, v[0:1]
	global_load_dword v96, v[2:3], off
	v_lshl_add_u64 v[2:3], v[66:67], 0, v[102:103]
	global_load_dwordx2 v[98:99], v[0:1], off nt
	s_waitcnt lgkmcnt(0)
	v_ashrrev_i32_e32 v1, 31, v78
	v_mov_b32_e32 v0, v78
	global_load_dwordx4 v[16:19], v[2:3], off nt
	v_lshl_add_u64 v[2:3], v[0:1], 2, s[44:45]
	v_lshlrev_b64 v[100:101], 12, v[0:1]
	v_lshlrev_b64 v[0:1], 11, v[0:1]
	ds_read2_b32 v[68:69], v194 offset0:112 offset1:120
	v_lshl_add_u64 v[0:1], v[72:73], 0, v[0:1]
	global_load_dword v90, v[2:3], off
	v_lshl_add_u64 v[2:3], v[66:67], 0, v[100:101]
	global_load_dwordx2 v[94:95], v[0:1], off nt
	v_ashrrev_i32_e32 v1, 31, v79
	v_mov_b32_e32 v0, v79
	global_load_dwordx4 v[12:15], v[2:3], off nt
	v_lshl_add_u64 v[2:3], v[0:1], 2, s[44:45]
	v_lshlrev_b64 v[88:89], 12, v[0:1]
	v_lshlrev_b64 v[0:1], 11, v[0:1]
	v_lshl_add_u64 v[0:1], v[72:73], 0, v[0:1]
	global_load_dword v82, v[2:3], off
	v_lshl_add_u64 v[2:3], v[66:67], 0, v[88:89]
	global_load_dwordx2 v[84:85], v[0:1], off nt
	s_waitcnt lgkmcnt(0)
	v_ashrrev_i32_e32 v1, 31, v68
	v_mov_b32_e32 v0, v68
	global_load_dwordx4 v[8:11], v[2:3], off nt
	v_lshl_add_u64 v[2:3], v[0:1], 2, s[44:45]
	v_lshlrev_b64 v[86:87], 12, v[0:1]
	v_lshlrev_b64 v[0:1], 11, v[0:1]
	v_lshl_add_u64 v[0:1], v[72:73], 0, v[0:1]
	v_ashrrev_i32_e32 v221, 31, v69
	v_mov_b32_e32 v220, v69
	global_load_dwordx2 v[80:81], v[0:1], off nt
	v_lshl_add_u64 v[0:1], v[220:221], 2, s[44:45]
	v_lshlrev_b64 v[74:75], 12, v[220:221]
	v_lshlrev_b64 v[220:221], 11, v[220:221]
	global_load_dword v76, v[2:3], off
	v_lshl_add_u64 v[2:3], v[66:67], 0, v[86:87]
	global_load_dword v70, v[0:1], off
	v_lshl_add_u64 v[0:1], v[66:67], 0, v[74:75]
	v_lshl_add_u64 v[72:73], v[72:73], 0, v[220:221]
	global_load_dwordx4 v[4:7], v[2:3], off nt
	v_add_u32_e32 v71, v153, v193
	global_load_dwordx4 v[0:3], v[0:1], off nt
	v_cmp_lt_i32_e32 vcc, v71, v145
	global_load_dwordx2 v[72:73], v[72:73], off nt
	s_and_saveexec_b64 s[4:5], vcc
	s_cbranch_execz .LBB0_430
	v_add_u32_e32 v71, 0xffff0000, v168
	v_lshrrev_b32_e32 v71, 14, v71
	v_add_u32_e32 v71, 16, v71
	v_ashrrev_i32_e32 v77, 12, v168
	v_cmp_gt_i32_e64 s[0:1], s33, v168
	ds_read_b64 v[224:225], v196
	s_waitcnt vmcnt(46)
	v_lshlrev_b32_e32 v228, 16, v182
	v_cndmask_b32_e64 v71, v71, v77, s[0:1]
	v_lshl_add_u32 v71, v71, 10, v195
	ds_read_b128 v[220:223], v71
	s_waitcnt lgkmcnt(1)
	v_lshlrev_b32_e32 v226, 16, v224
	v_and_b32_e32 v227, 0xffff0000, v224
	v_and_b32_e32 v229, 0xffff0000, v182
	v_pk_fma_f32 v[226:227], v[180:181], v[226:227], v[228:229] op_sel_hi:[0,1,1]
	s_waitcnt vmcnt(45) lgkmcnt(0)
	v_pk_fma_f32 v[60:61], v[220:221], v[226:227], v[60:61]
	v_lshlrev_b32_e32 v220, 16, v225
	v_and_b32_e32 v221, 0xffff0000, v225
	v_lshlrev_b32_e32 v182, 16, v183
	v_and_b32_e32 v183, 0xffff0000, v183
	v_lshl_add_u64 v[184:185], s[46:47], 0, v[184:185]
	v_pk_fma_f32 v[180:181], v[180:181], v[220:221], v[182:183] op_sel_hi:[0,1,1]
	v_lshl_add_u64 v[184:185], v[64:65], 2, v[184:185]
	v_pk_fma_f32 v[62:63], v[222:223], v[180:181], v[62:63]
	global_store_dwordx4 v[184:185], v[60:63], off

; DI void phase_moe(const Params& p, char* lds, int mode) {
;     ...
;           float4 ov[16]; u32x2 yv[16]; float gt[16]; int tk[16];
; #pragma unroll
;           for (int ps = 0; ps < 16; ++ps) {
;             const int grow = half * 128 + ps * 8 + (tid >> 5);
;             tk[ps] = rowtok[grow];
;             gt[ps] = gate[(size_t)k * T + tk[ps]];
;             ov[ps] = *(const float4*)(p.out + (size_t)tk[ps] * D + col);
;             yv[ps] = *(const u32x2*)(Y0 + (size_t)tk[ps] * D + col);
;           }
.LBB0_460:
	s_or_b64 exec, exec, s[64:65]
	ds_read2_b32 v[172:173], v194 offset1:8
	s_waitcnt vmcnt(1)
	v_or_b32_e32 v0, 0x80, v64
	v_ashrrev_i32_e32 v1, 31, v0
	v_lshlrev_b64 v[184:185], 1, v[0:1]
	s_waitcnt lgkmcnt(0)
	v_ashrrev_i32_e32 v3, 31, v172
	v_mov_b32_e32 v2, v172
	v_lshl_add_u64 v[4:5], v[2:3], 2, s[44:45]
	v_lshlrev_b64 v[182:183], 12, v[2:3]
	v_lshlrev_b64 v[2:3], 11, v[2:3]
	v_lshl_add_u64 v[2:3], s[42:43], 0, v[2:3]
	global_load_dword v178, v[4:5], off
	v_lshl_add_u64 v[4:5], v[66:67], 0, v[182:183]
	v_lshl_add_u64 v[0:1], v[2:3], 0, v[184:185]
	v_ashrrev_i32_e32 v3, 31, v173
	v_mov_b32_e32 v2, v173
	global_load_dwordx4 v[60:63], v[4:5], off offset:512 nt
	v_lshl_add_u64 v[4:5], v[2:3], 2, s[44:45]
	global_load_dwordx2 v[180:181], v[0:1], off nt
	global_load_dword v170, v[4:5], off
	ds_read2_b32 v[158:159], v194 offset0:16 offset1:24
	v_lshlrev_b64 v[176:177], 12, v[2:3]
	v_lshl_add_u64 v[0:1], v[66:67], 0, v[176:177]
	global_load_dwordx4 v[56:59], v[0:1], off offset:512 nt
	v_lshlrev_b64 v[0:1], 11, v[2:3]
	v_lshl_add_u64 v[0:1], s[42:43], 0, v[0:1]
	s_waitcnt lgkmcnt(0)
	v_ashrrev_i32_e32 v3, 31, v158
	v_mov_b32_e32 v2, v158
	v_lshl_add_u64 v[0:1], v[0:1], 0, v[184:185]
	v_lshlrev_b64 v[168:169], 12, v[2:3]
	v_lshl_add_u64 v[4:5], v[2:3], 2, s[44:45]
	global_load_dwordx2 v[174:175], v[0:1], off nt
	global_load_dword v164, v[4:5], off
	v_lshl_add_u64 v[0:1], v[66:67], 0, v[168:169]
	global_load_dwordx4 v[52:55], v[0:1], off offset:512 nt
	v_lshlrev_b64 v[0:1], 11, v[2:3]
	v_lshl_add_u64 v[0:1], s[42:43], 0, v[0:1]
	v_lshl_add_u64 v[0:1], v[0:1], 0, v[184:185]
	v_ashrrev_i32_e32 v3, 31, v159
	v_mov_b32_e32 v2, v159
	v_lshl_add_u64 v[4:5], v[2:3], 2, s[44:45]
	global_load_dwordx2 v[166:167], v[0:1], off nt
	global_load_dword v156, v[4:5], off
	ds_read2_b32 v[144:145], v194 offset0:32 offset1:40
	v_lshlrev_b64 v[162:163], 12, v[2:3]
	v_lshl_add_u64 v[0:1], v[66:67], 0, v[162:163]
	global_load_dwordx4 v[48:51], v[0:1], off offset:512 nt
	v_lshlrev_b64 v[0:1], 11, v[2:3]
	v_lshl_add_u64 v[0:1], s[42:43], 0, v[0:1]
	s_waitcnt lgkmcnt(0)
	v_ashrrev_i32_e32 v3, 31, v144
	v_mov_b32_e32 v2, v144
	v_lshl_add_u64 v[0:1], v[0:1], 0, v[184:185]
	v_lshlrev_b64 v[154:155], 12, v[2:3]
	v_lshl_add_u64 v[4:5], v[2:3], 2, s[44:45]
	global_load_dwordx2 v[160:161], v[0:1], off nt
	global_load_dword v150, v[4:5], off
	v_lshl_add_u64 v[0:1], v[66:67], 0, v[154:155]
	global_load_dwordx4 v[44:47], v[0:1], off offset:512 nt
	v_lshlrev_b64 v[0:1], 11, v[2:3]
	v_lshl_add_u64 v[0:1], s[42:43], 0, v[0:1]
	v_lshl_add_u64 v[0:1], v[0:1], 0, v[184:185]
	v_ashrrev_i32_e32 v3, 31, v145
	v_mov_b32_e32 v2, v145
	v_lshl_add_u64 v[4:5], v[2:3], 2, s[44:45]
	global_load_dwordx2 v[152:153], v[0:1], off nt
	global_load_dword v142, v[4:5], off
	ds_read2_b32 v[124:125], v194 offset0:48 offset1:56
	v_lshlrev_b64 v[148:149], 12, v[2:3]
	v_lshl_add_u64 v[0:1], v[66:67], 0, v[148:149]
	global_load_dwordx4 v[40:43], v[0:1], off offset:512 nt
	v_lshlrev_b64 v[0:1], 11, v[2:3]
	v_lshl_add_u64 v[0:1], s[42:43], 0, v[0:1]
	s_waitcnt lgkmcnt(0)
	v_ashrrev_i32_e32 v3, 31, v124
	v_mov_b32_e32 v2, v124
	v_lshl_add_u64 v[0:1], v[0:1], 0, v[184:185]
	v_lshlrev_b64 v[140:141], 12, v[2:3]
	v_lshl_add_u64 v[4:5], v[2:3], 2, s[44:45]
	global_load_dwordx2 v[146:147], v[0:1], off nt
	global_load_dword v128, v[4:5], off
	v_lshl_add_u64 v[0:1], v[66:67], 0, v[140:141]
	global_load_dwordx4 v[36:39], v[0:1], off offset:512 nt
	v_lshlrev_b64 v[0:1], 11, v[2:3]
	v_lshl_add_u64 v[0:1], s[42:43], 0, v[0:1]
	v_lshl_add_u64 v[0:1], v[0:1], 0, v[184:185]
	v_ashrrev_i32_e32 v3, 31, v125
	v_mov_b32_e32 v2, v125
	v_lshl_add_u64 v[4:5], v[2:3], 2, s[44:45]
	global_load_dwordx2 v[138:139], v[0:1], off nt
	global_load_dword v122, v[4:5], off
	ds_read2_b32 v[110:111], v194 offset0:64 offset1:72
	v_lshlrev_b64 v[136:137], 12, v[2:3]
	v_lshl_add_u64 v[0:1], v[66:67], 0, v[136:137]
	global_load_dwordx4 v[32:35], v[0:1], off offset:512 nt
	v_lshlrev_b64 v[0:1], 11, v[2:3]
	v_lshl_add_u64 v[0:1], s[42:43], 0, v[0:1]
	s_waitcnt lgkmcnt(0)
; DI void phase_moe(const Params& p, char* lds, int mode) {
;     ...
;           float4 ov[16]; u32x2 yv[16]; float gt[16]; int tk[16];
; #pragma unroll
;           for (int ps = 0; ps < 16; ++ps) {
;             const int grow = half * 128 + ps * 8 + (tid >> 5);
;             tk[ps] = rowtok[grow];
;             gt[ps] = gate[(size_t)k * T + tk[ps]];
;             ov[ps] = *(const float4*)(p.out + (size_t)tk[ps] * D + col);
;             yv[ps] = *(const u32x2*)(Y0 + (size_t)tk[ps] * D + col);
;           }
	v_ashrrev_i32_e32 v3, 31, v110
	v_mov_b32_e32 v2, v110
	v_lshl_add_u64 v[0:1], v[0:1], 0, v[184:185]
	v_lshlrev_b64 v[120:121], 12, v[2:3]
	v_lshl_add_u64 v[4:5], v[2:3], 2, s[44:45]
	global_load_dwordx2 v[126:127], v[0:1], off nt
	global_load_dword v116, v[4:5], off
	v_lshl_add_u64 v[0:1], v[66:67], 0, v[120:121]
	global_load_dwordx4 v[28:31], v[0:1], off offset:512 nt
	v_lshlrev_b64 v[0:1], 11, v[2:3]
	v_lshl_add_u64 v[0:1], s[42:43], 0, v[0:1]
	v_lshl_add_u64 v[0:1], v[0:1], 0, v[184:185]
	v_ashrrev_i32_e32 v3, 31, v111
	v_mov_b32_e32 v2, v111
	v_lshl_add_u64 v[4:5], v[2:3], 2, s[44:45]
	global_load_dwordx2 v[118:119], v[0:1], off nt
	global_load_dword v108, v[4:5], off
	ds_read2_b32 v[96:97], v194 offset0:80 offset1:88
	v_lshlrev_b64 v[114:115], 12, v[2:3]
	v_lshl_add_u64 v[0:1], v[66:67], 0, v[114:115]
	global_load_dwordx4 v[24:27], v[0:1], off offset:512 nt
	v_lshlrev_b64 v[0:1], 11, v[2:3]
	v_lshl_add_u64 v[0:1], s[42:43], 0, v[0:1]
	s_waitcnt lgkmcnt(0)
	v_ashrrev_i32_e32 v3, 31, v96
	v_mov_b32_e32 v2, v96
	v_lshl_add_u64 v[0:1], v[0:1], 0, v[184:185]
	v_lshlrev_b64 v[106:107], 12, v[2:3]
	v_lshl_add_u64 v[4:5], v[2:3], 2, s[44:45]
	global_load_dwordx2 v[112:113], v[0:1], off nt
	global_load_dword v102, v[4:5], off
	v_lshl_add_u64 v[0:1], v[66:67], 0, v[106:107]
	global_load_dwordx4 v[20:23], v[0:1], off offset:512 nt
	v_lshlrev_b64 v[0:1], 11, v[2:3]
	v_lshl_add_u64 v[0:1], s[42:43], 0, v[0:1]
	v_lshl_add_u64 v[0:1], v[0:1], 0, v[184:185]
	v_ashrrev_i32_e32 v3, 31, v97
	v_mov_b32_e32 v2, v97
	v_lshl_add_u64 v[4:5], v[2:3], 2, s[44:45]
	global_load_dwordx2 v[104:105], v[0:1], off nt
	global_load_dword v94, v[4:5], off
	ds_read2_b32 v[82:83], v194 offset0:96 offset1:104
	v_lshlrev_b64 v[100:101], 12, v[2:3]
	v_lshl_add_u64 v[0:1], v[66:67], 0, v[100:101]
	global_load_dwordx4 v[16:19], v[0:1], off offset:512 nt
	v_lshlrev_b64 v[0:1], 11, v[2:3]
	v_lshl_add_u64 v[0:1], s[42:43], 0, v[0:1]
	s_waitcnt lgkmcnt(0)
	v_ashrrev_i32_e32 v3, 31, v82
	v_mov_b32_e32 v2, v82
	v_lshl_add_u64 v[0:1], v[0:1], 0, v[184:185]
	v_lshlrev_b64 v[92:93], 12, v[2:3]
	v_lshl_add_u64 v[4:5], v[2:3], 2, s[44:45]
	global_load_dwordx2 v[98:99], v[0:1], off nt
	global_load_dword v88, v[4:5], off
	v_lshl_add_u64 v[0:1], v[66:67], 0, v[92:93]
	global_load_dwordx4 v[12:15], v[0:1], off offset:512 nt
	v_lshlrev_b64 v[0:1], 11, v[2:3]
	v_lshl_add_u64 v[0:1], s[42:43], 0, v[0:1]
	v_lshl_add_u64 v[0:1], v[0:1], 0, v[184:185]
	v_ashrrev_i32_e32 v3, 31, v83
	v_mov_b32_e32 v2, v83
	v_lshl_add_u64 v[4:5], v[2:3], 2, s[44:45]
	global_load_dwordx2 v[90:91], v[0:1], off nt
	global_load_dword v80, v[4:5], off
	ds_read2_b32 v[70:71], v194 offset0:112 offset1:120
	v_lshlrev_b64 v[86:87], 12, v[2:3]
	v_lshl_add_u64 v[0:1], v[66:67], 0, v[86:87]
	global_load_dwordx4 v[8:11], v[0:1], off offset:512 nt
	v_lshlrev_b64 v[0:1], 11, v[2:3]
	v_lshl_add_u64 v[0:1], s[42:43], 0, v[0:1]
	s_waitcnt lgkmcnt(0)
	v_ashrrev_i32_e32 v3, 31, v70
	v_mov_b32_e32 v2, v70
	v_lshl_add_u64 v[0:1], v[0:1], 0, v[184:185]
	v_lshlrev_b64 v[78:79], 12, v[2:3]
	v_lshl_add_u64 v[4:5], v[2:3], 2, s[44:45]
	global_load_dwordx2 v[84:85], v[0:1], off nt
	global_load_dword v74, v[4:5], off
	v_lshl_add_u64 v[0:1], v[66:67], 0, v[78:79]
	global_load_dwordx4 v[4:7], v[0:1], off offset:512 nt
	v_lshlrev_b64 v[0:1], 11, v[2:3]
	v_lshl_add_u64 v[0:1], s[42:43], 0, v[0:1]
	v_ashrrev_i32_e32 v221, 31, v71
	v_mov_b32_e32 v220, v71
	v_lshl_add_u64 v[0:1], v[0:1], 0, v[184:185]
	s_waitcnt vmcnt(44)
	v_lshlrev_b64 v[72:73], 12, v[220:221]
	v_lshl_add_u64 v[2:3], v[220:221], 2, s[44:45]
	global_load_dwordx2 v[76:77], v[0:1], off nt
	global_load_dword v68, v[2:3], off
	v_lshl_add_u64 v[0:1], v[66:67], 0, v[72:73]
	v_lshlrev_b64 v[66:67], 11, v[220:221]
	v_lshl_add_u64 v[66:67], s[42:43], 0, v[66:67]
	v_lshl_add_u64 v[66:67], v[66:67], 0, v[184:185]
	global_load_dwordx4 v[0:3], v[0:1], off offset:512 nt
	s_nop 0
	global_load_dwordx2 v[66:67], v[66:67], off nt
	s_and_saveexec_b64 s[36:37], vcc
	s_cbranch_execnz .LBB0_476
	s_or_b64 exec, exec, s[36:37]
	s_and_saveexec_b64 s[36:37], s[0:1]
	s_cbranch_execnz .LBB0_477
